# skip the K-loop trailing barrier in each unit's last iteration: leading half starts epilogue/next loads during trailing half's last MFMA block
# baseline (speedup 1.0000x reference)
; #define PG8_STAGE(bufoff, gbase, voff) do { _Pragma("unroll") for (int _i = 0; _i < 2; ++_i) \
;         __builtin_amdgcn_global_load_lds((const unsigned*)((const char*)(gbase) + (voff)[_i]), (PG8_LAS unsigned*)(lds + (bufoff) + ldsw + _i * 8192), 16, 0, 0); } while (0)
; #define PG8_LDA(dst, b, h) do { _Pragma("unroll") for (int m = 0; m < 4; ++m) _Pragma("unroll") for (int k = 0; k < 2; ++k) dst[m][k] = *(const PG8_LAS bf16x8*)(lds + PG8_SA(b, h) + aoff + m * 2048 + k * 1024); } while (0)
; #define PG8_LDB(dst, b, h) do { _Pragma("unroll") for (int n = 0; n < 2; ++n) _Pragma("unroll") for (int k = 0; k < 2; ++k) dst[n][k] = *(const PG8_LAS bf16x8*)(lds + PG8_SB(b, h) + boff + n * 2048 + k * 1024); } while (0)
; #define PG8_MMA(ai, bj, At, Bt) do { __builtin_amdgcn_s_setprio(1); _Pragma("unroll") for (int m = 0; m < 4; ++m) _Pragma("unroll") for (int n = 0; n < 2; ++n) _Pragma("unroll") for (int k = 0; k < 2; ++k) \
;         acc[ai][bj][m][n] = __builtin_amdgcn_mfma_f32_16x16x32_bf16(Bt[n][k], At[m][k], acc[ai][bj][m][n], 0, 0, 0); __builtin_amdgcn_s_setprio(0); } while (0)
; #define PG8_WAIT_V(n) asm volatile("s_waitcnt vmcnt(" #n ")" ::: "memory")
; #define PG8_WAIT_L(n) asm volatile("s_waitcnt lgkmcnt(" #n ")" ::: "memory")
; template <class Epi, class Sched, bool ALIGN_EPI = false, bool SP2 = false>
; __device__ __forceinline__ void gemm_phase(PG8_LAS unsigned char* lds, const Gemm g, const Sched& S, const Epi& E) {
;     ...
;             const bool last = (t == nt - 2);
;             const char* a1 = cA + (size_t)(t + 1) * kstep;
;             const char* a2 = last ? nA : cA + (size_t)(t + 2) * kstep; const char* b2 = last ? nB : cB + (size_t)(t + 2) * kstep;
;             const char* a3 = a2 + kstep; const char* b3 = b2 + kstep;
;             if (last && has_next) S.a_ready(nxt);
;             if constexpr (SP2) {
;             PG8_LDB(B0, 0, 0); PG8_LDB(B1, 0, 1); PG8_SCHED; PG8_LDA(At, 0, 0); PG8_STAGE(PG8_SA(1, 1), a1 + hstep, voffA);
;             PG8_WAIT_V(8); PG8_WAIT_L(0); PG8_BAR; PG8_MMA(0, 0, At, B0); PG8_MMA(0, 1, At, B1); PG8_BAR; PG8_SCHED;
;             PG8_LDA(At, 0, 1); PG8_STAGE(PG8_SB(0, 0), b2, voffB); PG8_STAGE(PG8_SB(0, 1), b2 + hstep, voffB); PG8_STAGE(PG8_SA(0, 0), a2, voffA);
;             PG8_WAIT_V(8); PG8_WAIT_L(0); PG8_BAR; PG8_MMA(1, 0, At, B0); PG8_MMA(1, 1, At, B1); PG8_BAR; PG8_SCHED;
.LBB0_63:
	s_add_i32 s66, s46, 2
	s_add_u32 s10, s44, 0x80
	s_addc_u32 s11, s45, 0
	s_add_i32 s67, 0, 0x10000
	s_cmp_eq_u32 s74, s46
	s_cselect_b32 s47, s63, s11
	s_cselect_b32 s46, s62, s10
	s_cselect_b32 s79, s65, s20
	s_cselect_b32 s78, s64, s19
	s_add_i32 s10, 0, 0x14000
	v_add_u32_e32 v140, s67, v183
	v_add_u32_e32 v166, s10, v183
	ds_read_b128 v[128:131], v140
	ds_read_b128 v[132:135], v140 offset:1024
	ds_read_b128 v[136:139], v140 offset:2048
	ds_read_b128 v[140:143], v140 offset:3072
	ds_read_b128 v[144:147], v166
	ds_read_b128 v[148:151], v166 offset:1024
	ds_read_b128 v[152:155], v166 offset:2048
	ds_read_b128 v[166:169], v166 offset:3072
	v_lshl_add_u64 v[190:191], s[44:45], 0, v[162:163]
	s_add_i32 m0, s23, 0xc000
	ds_read_b128 v[170:173], v185
	ds_read_b128 v[174:177], v185 offset:1024
	ds_read_b128 v[178:181], v185 offset:2048
	ds_read_b128 v[186:189], v185 offset:3072
	ds_read_b128 v[194:197], v185 offset:4096
	ds_read_b128 v[198:201], v185 offset:5120
	ds_read_b128 v[202:205], v185 offset:6144
	ds_read_b128 v[206:209], v185 offset:7168
	global_load_lds_dwordx4 v[190:191], off
	v_lshl_add_u64 v[190:191], s[44:45], 0, v[164:165]
	s_add_i32 m0, s23, 0xe000
	s_nop 0
	global_load_lds_dwordx4 v[190:191], off
	s_waitcnt vmcnt(8)
	s_waitcnt lgkmcnt(0)
	s_barrier
	s_setprio 1
	s_waitcnt lgkmcnt(0)
	v_mfma_f32_16x16x32_bf16 v[124:127], v[128:131], v[170:173], v[124:127]
	v_mfma_f32_16x16x32_bf16 v[120:123], v[136:139], v[170:173], v[120:123]
	v_mfma_f32_16x16x32_bf16 v[108:111], v[128:131], v[178:181], v[108:111]
	v_mfma_f32_16x16x32_bf16 v[104:107], v[136:139], v[178:181], v[104:107]
	v_mfma_f32_16x16x32_bf16 v[92:95], v[128:131], v[194:197], v[92:95]
	v_mfma_f32_16x16x32_bf16 v[88:91], v[136:139], v[194:197], v[88:91]
	v_mfma_f32_16x16x32_bf16 v[76:79], v[128:131], v[202:205], v[76:79]
	v_mfma_f32_16x16x32_bf16 v[72:75], v[136:139], v[202:205], v[72:75]
	v_mfma_f32_16x16x32_bf16 v[124:127], v[132:135], v[174:177], v[124:127]
	v_mfma_f32_16x16x32_bf16 v[120:123], v[140:143], v[174:177], v[120:123]
	v_mfma_f32_16x16x32_bf16 v[108:111], v[132:135], v[186:189], v[108:111]
	v_mfma_f32_16x16x32_bf16 v[104:107], v[140:143], v[186:189], v[104:107]
	v_mfma_f32_16x16x32_bf16 v[92:95], v[132:135], v[198:201], v[92:95]
	v_mfma_f32_16x16x32_bf16 v[88:91], v[140:143], v[198:201], v[88:91]
	v_mfma_f32_16x16x32_bf16 v[76:79], v[132:135], v[206:209], v[76:79]
	v_mfma_f32_16x16x32_bf16 v[72:75], v[140:143], v[206:209], v[72:75]
	s_setprio 0
	s_setprio 1
	v_mfma_f32_16x16x32_bf16 v[116:119], v[144:147], v[170:173], v[116:119]
	v_mfma_f32_16x16x32_bf16 v[112:115], v[152:155], v[170:173], v[112:115]
	v_mfma_f32_16x16x32_bf16 v[100:103], v[144:147], v[178:181], v[100:103]
	v_mfma_f32_16x16x32_bf16 v[96:99], v[152:155], v[178:181], v[96:99]
	v_mfma_f32_16x16x32_bf16 v[84:87], v[144:147], v[194:197], v[84:87]
	v_mfma_f32_16x16x32_bf16 v[80:83], v[152:155], v[194:197], v[80:83]
	v_mfma_f32_16x16x32_bf16 v[68:71], v[144:147], v[202:205], v[68:71]
	v_mfma_f32_16x16x32_bf16 v[64:67], v[152:155], v[202:205], v[64:67]
	v_mfma_f32_16x16x32_bf16 v[116:119], v[148:151], v[174:177], v[116:119]
	v_mfma_f32_16x16x32_bf16 v[112:115], v[166:169], v[174:177], v[112:115]
	v_mfma_f32_16x16x32_bf16 v[100:103], v[148:151], v[186:189], v[100:103]
	v_mfma_f32_16x16x32_bf16 v[96:99], v[166:169], v[186:189], v[96:99]
	v_mfma_f32_16x16x32_bf16 v[84:87], v[148:151], v[198:201], v[84:87]
	v_mfma_f32_16x16x32_bf16 v[80:83], v[166:169], v[198:201], v[80:83]
	v_mfma_f32_16x16x32_bf16 v[68:71], v[148:151], v[206:209], v[68:71]
	v_mfma_f32_16x16x32_bf16 v[64:67], v[166:169], v[206:209], v[64:67]
	s_setprio 0
	s_barrier
	s_add_i32 s11, s67, s22
	v_lshl_add_u64 v[190:191], s[78:79], 0, v[192:193]
	s_mov_b32 m0, s11
	ds_read_b128 v[170:173], v185 offset:16384
	ds_read_b128 v[174:177], v185 offset:17408
	ds_read_b128 v[178:181], v185 offset:18432
	ds_read_b128 v[186:189], v185 offset:19456
	ds_read_b128 v[194:197], v185 offset:20480
	ds_read_b128 v[198:201], v185 offset:21504
	ds_read_b128 v[202:205], v185 offset:22528
	ds_read_b128 v[206:209], v185 offset:23552
	global_load_lds_dwordx4 v[190:191], off
	s_add_i32 m0, s11, 0x2000
	v_lshl_add_u64 v[210:211], s[78:79], 0, v[160:161]
	s_add_u32 s78, s78, s52
	s_addc_u32 s79, s79, 0
	s_add_i32 s10, s10, s22
	global_load_lds_dwordx4 v[210:211], off
	v_lshl_add_u64 v[212:213], s[78:79], 0, v[192:193]
	s_mov_b32 m0, s10
	v_lshl_add_u64 v[214:215], s[78:79], 0, v[160:161]
	global_load_lds_dwordx4 v[212:213], off
	s_add_i32 m0, s10, 0x2000
	v_lshl_add_u64 v[216:217], s[46:47], 0, v[156:157]
	global_load_lds_dwordx4 v[214:215], off
	s_mov_b32 m0, s23
	v_lshl_add_u64 v[218:219], s[46:47], 0, v[158:159]
	global_load_lds_dwordx4 v[216:217], off
	s_mov_b32 m0, s51
	s_nop 0
	global_load_lds_dwordx4 v[218:219], off
	s_waitcnt vmcnt(8)
	s_waitcnt lgkmcnt(0)
	s_barrier
; #define PG8_STAGE(bufoff, gbase, voff) do { _Pragma("unroll") for (int _i = 0; _i < 2; ++_i) \
;         __builtin_amdgcn_global_load_lds((const unsigned*)((const char*)(gbase) + (voff)[_i]), (PG8_LAS unsigned*)(lds + (bufoff) + ldsw + _i * 8192), 16, 0, 0); } while (0)
; #define PG8_LDA(dst, b, h) do { _Pragma("unroll") for (int m = 0; m < 4; ++m) _Pragma("unroll") for (int k = 0; k < 2; ++k) dst[m][k] = *(const PG8_LAS bf16x8*)(lds + PG8_SA(b, h) + aoff + m * 2048 + k * 1024); } while (0)
; #define PG8_LDB(dst, b, h) do { _Pragma("unroll") for (int n = 0; n < 2; ++n) _Pragma("unroll") for (int k = 0; k < 2; ++k) dst[n][k] = *(const PG8_LAS bf16x8*)(lds + PG8_SB(b, h) + boff + n * 2048 + k * 1024); } while (0)
; #define PG8_MMA(ai, bj, At, Bt) do { __builtin_amdgcn_s_setprio(1); _Pragma("unroll") for (int m = 0; m < 4; ++m) _Pragma("unroll") for (int n = 0; n < 2; ++n) _Pragma("unroll") for (int k = 0; k < 2; ++k) \
;         acc[ai][bj][m][n] = __builtin_amdgcn_mfma_f32_16x16x32_bf16(Bt[n][k], At[m][k], acc[ai][bj][m][n], 0, 0, 0); __builtin_amdgcn_s_setprio(0); } while (0)
; #define PG8_WAIT_V(n) asm volatile("s_waitcnt vmcnt(" #n ")" ::: "memory")
; #define PG8_WAIT_L(n) asm volatile("s_waitcnt lgkmcnt(" #n ")" ::: "memory")
; #define PG8_BAR __builtin_amdgcn_s_barrier()
; #define PG8_SCHED __builtin_amdgcn_sched_barrier(0)
; template <class Epi, class Sched, bool ALIGN_EPI = false, bool SP2 = false>
; __device__ __forceinline__ void gemm_phase(PG8_LAS unsigned char* lds, const Gemm g, const Sched& S, const Epi& E) {
;     ...
;             PG8_WAIT_V(8); PG8_WAIT_L(0); PG8_BAR; PG8_MMA(1, 0, At, B0); PG8_MMA(1, 1, At, B1); PG8_BAR; PG8_SCHED;
;             PG8_LDB(B0, 1, 0); PG8_LDB(B1, 1, 1); PG8_SCHED; PG8_LDA(At, 1, 0); PG8_STAGE(PG8_SA(0, 1), a2 + hstep, voffA);
;             PG8_WAIT_V(8); PG8_WAIT_L(0); PG8_BAR; PG8_MMA(0, 0, At, B0); PG8_MMA(0, 1, At, B1); PG8_BAR; PG8_SCHED;
	s_setprio 1
	s_waitcnt lgkmcnt(0)
	v_mfma_f32_16x16x32_bf16 v[60:63], v[128:131], v[170:173], v[60:63]
	v_mfma_f32_16x16x32_bf16 v[56:59], v[136:139], v[170:173], v[56:59]
	v_mfma_f32_16x16x32_bf16 v[44:47], v[128:131], v[178:181], v[44:47]
	v_mfma_f32_16x16x32_bf16 v[40:43], v[136:139], v[178:181], v[40:43]
	v_mfma_f32_16x16x32_bf16 v[28:31], v[128:131], v[194:197], v[28:31]
	v_mfma_f32_16x16x32_bf16 v[24:27], v[136:139], v[194:197], v[24:27]
	v_mfma_f32_16x16x32_bf16 v[12:15], v[128:131], v[202:205], v[12:15]
	v_mfma_f32_16x16x32_bf16 v[8:11], v[136:139], v[202:205], v[8:11]
	v_mfma_f32_16x16x32_bf16 v[60:63], v[132:135], v[174:177], v[60:63]
	v_mfma_f32_16x16x32_bf16 v[56:59], v[140:143], v[174:177], v[56:59]
	v_mfma_f32_16x16x32_bf16 v[44:47], v[132:135], v[186:189], v[44:47]
	v_mfma_f32_16x16x32_bf16 v[40:43], v[140:143], v[186:189], v[40:43]
	v_mfma_f32_16x16x32_bf16 v[28:31], v[132:135], v[198:201], v[28:31]
	v_mfma_f32_16x16x32_bf16 v[24:27], v[140:143], v[198:201], v[24:27]
	v_mfma_f32_16x16x32_bf16 v[12:15], v[132:135], v[206:209], v[12:15]
	v_mfma_f32_16x16x32_bf16 v[8:11], v[140:143], v[206:209], v[8:11]
	s_setprio 0
	s_setprio 1
	v_mfma_f32_16x16x32_bf16 v[52:55], v[144:147], v[170:173], v[52:55]
	v_mfma_f32_16x16x32_bf16 v[48:51], v[152:155], v[170:173], v[48:51]
	v_mfma_f32_16x16x32_bf16 v[36:39], v[144:147], v[178:181], v[36:39]
	v_mfma_f32_16x16x32_bf16 v[32:35], v[152:155], v[178:181], v[32:35]
	v_mfma_f32_16x16x32_bf16 v[20:23], v[144:147], v[194:197], v[20:23]
	v_mfma_f32_16x16x32_bf16 v[16:19], v[152:155], v[194:197], v[16:19]
	v_mfma_f32_16x16x32_bf16 v[4:7], v[144:147], v[202:205], v[4:7]
	v_mfma_f32_16x16x32_bf16 v[0:3], v[152:155], v[202:205], v[0:3]
	v_mfma_f32_16x16x32_bf16 v[52:55], v[148:151], v[174:177], v[52:55]
	v_mfma_f32_16x16x32_bf16 v[48:51], v[166:169], v[174:177], v[48:51]
	v_mfma_f32_16x16x32_bf16 v[36:39], v[148:151], v[186:189], v[36:39]
	v_mfma_f32_16x16x32_bf16 v[32:35], v[166:169], v[186:189], v[32:35]
	v_mfma_f32_16x16x32_bf16 v[20:23], v[148:151], v[198:201], v[20:23]
	v_mfma_f32_16x16x32_bf16 v[16:19], v[166:169], v[198:201], v[16:19]
	v_mfma_f32_16x16x32_bf16 v[4:7], v[148:151], v[206:209], v[4:7]
	v_mfma_f32_16x16x32_bf16 v[0:3], v[166:169], v[206:209], v[0:3]
	s_setprio 0
	s_barrier
	s_add_i32 s10, 0, 0x18000
	s_add_i32 s11, 0, 0x1c000
	v_add_u32_e32 v140, s10, v183
	v_add_u32_e32 v166, s11, v183
	ds_read_b128 v[128:131], v140
	ds_read_b128 v[132:135], v140 offset:1024
	ds_read_b128 v[136:139], v140 offset:2048
	ds_read_b128 v[140:143], v140 offset:3072
	ds_read_b128 v[144:147], v166
	ds_read_b128 v[148:151], v166 offset:1024
	ds_read_b128 v[152:155], v166 offset:2048
	ds_read_b128 v[166:169], v166 offset:3072
	s_add_u32 s46, s46, s52
	s_addc_u32 s47, s47, 0
	s_mov_b32 m0, s68
	v_lshl_add_u64 v[220:221], s[46:47], 0, v[156:157]
	ds_read_b128 v[170:173], v185 offset:32768
	ds_read_b128 v[174:177], v185 offset:33792
	ds_read_b128 v[178:181], v185 offset:34816
	ds_read_b128 v[186:189], v185 offset:35840
	ds_read_b128 v[194:197], v185 offset:36864
	ds_read_b128 v[198:201], v185 offset:37888
	ds_read_b128 v[202:205], v185 offset:38912
	ds_read_b128 v[206:209], v185 offset:39936
	global_load_lds_dwordx4 v[220:221], off
	v_lshl_add_u64 v[220:221], s[46:47], 0, v[158:159]
	s_mov_b32 m0, s69
	s_nop 0
	global_load_lds_dwordx4 v[220:221], off
	s_waitcnt vmcnt(8)
	s_waitcnt lgkmcnt(0)
	s_barrier
	s_setprio 1
	s_waitcnt lgkmcnt(0)
	v_mfma_f32_16x16x32_bf16 v[124:127], v[128:131], v[170:173], v[124:127]
	v_mfma_f32_16x16x32_bf16 v[120:123], v[136:139], v[170:173], v[120:123]
	v_mfma_f32_16x16x32_bf16 v[108:111], v[128:131], v[178:181], v[108:111]
	v_mfma_f32_16x16x32_bf16 v[104:107], v[136:139], v[178:181], v[104:107]
	v_mfma_f32_16x16x32_bf16 v[92:95], v[128:131], v[194:197], v[92:95]
	v_mfma_f32_16x16x32_bf16 v[88:91], v[136:139], v[194:197], v[88:91]
	v_mfma_f32_16x16x32_bf16 v[76:79], v[128:131], v[202:205], v[76:79]
	v_mfma_f32_16x16x32_bf16 v[72:75], v[136:139], v[202:205], v[72:75]
	v_mfma_f32_16x16x32_bf16 v[124:127], v[132:135], v[174:177], v[124:127]
	v_mfma_f32_16x16x32_bf16 v[120:123], v[140:143], v[174:177], v[120:123]
	v_mfma_f32_16x16x32_bf16 v[108:111], v[132:135], v[186:189], v[108:111]
	v_mfma_f32_16x16x32_bf16 v[104:107], v[140:143], v[186:189], v[104:107]
	v_mfma_f32_16x16x32_bf16 v[92:95], v[132:135], v[198:201], v[92:95]
	v_mfma_f32_16x16x32_bf16 v[88:91], v[140:143], v[198:201], v[88:91]
	v_mfma_f32_16x16x32_bf16 v[76:79], v[132:135], v[206:209], v[76:79]
	v_mfma_f32_16x16x32_bf16 v[72:75], v[140:143], v[206:209], v[72:75]
	s_setprio 0
	s_setprio 1
	v_mfma_f32_16x16x32_bf16 v[116:119], v[144:147], v[170:173], v[116:119]
	v_mfma_f32_16x16x32_bf16 v[112:115], v[152:155], v[170:173], v[112:115]
	v_mfma_f32_16x16x32_bf16 v[100:103], v[144:147], v[178:181], v[100:103]
	v_mfma_f32_16x16x32_bf16 v[96:99], v[152:155], v[178:181], v[96:99]
	v_mfma_f32_16x16x32_bf16 v[84:87], v[144:147], v[194:197], v[84:87]
	v_mfma_f32_16x16x32_bf16 v[80:83], v[152:155], v[194:197], v[80:83]
	v_mfma_f32_16x16x32_bf16 v[68:71], v[144:147], v[202:205], v[68:71]
	v_mfma_f32_16x16x32_bf16 v[64:67], v[152:155], v[202:205], v[64:67]
	v_mfma_f32_16x16x32_bf16 v[116:119], v[148:151], v[174:177], v[116:119]
	v_mfma_f32_16x16x32_bf16 v[112:115], v[166:169], v[174:177], v[112:115]
	v_mfma_f32_16x16x32_bf16 v[100:103], v[148:151], v[186:189], v[100:103]
	v_mfma_f32_16x16x32_bf16 v[96:99], v[166:169], v[186:189], v[96:99]
	v_mfma_f32_16x16x32_bf16 v[84:87], v[148:151], v[198:201], v[84:87]
	v_mfma_f32_16x16x32_bf16 v[80:83], v[166:169], v[198:201], v[80:83]
	v_mfma_f32_16x16x32_bf16 v[68:71], v[148:151], v[206:209], v[68:71]
	v_mfma_f32_16x16x32_bf16 v[64:67], v[166:169], v[206:209], v[64:67]
	s_setprio 0
	s_barrier
; #define PG8_STAGE(bufoff, gbase, voff) do { _Pragma("unroll") for (int _i = 0; _i < 2; ++_i) \
;         __builtin_amdgcn_global_load_lds((const unsigned*)((const char*)(gbase) + (voff)[_i]), (PG8_LAS unsigned*)(lds + (bufoff) + ldsw + _i * 8192), 16, 0, 0); } while (0)
; #define PG8_LDA(dst, b, h) do { _Pragma("unroll") for (int m = 0; m < 4; ++m) _Pragma("unroll") for (int k = 0; k < 2; ++k) dst[m][k] = *(const PG8_LAS bf16x8*)(lds + PG8_SA(b, h) + aoff + m * 2048 + k * 1024); } while (0)
; #define PG8_MMA(ai, bj, At, Bt) do { __builtin_amdgcn_s_setprio(1); _Pragma("unroll") for (int m = 0; m < 4; ++m) _Pragma("unroll") for (int n = 0; n < 2; ++n) _Pragma("unroll") for (int k = 0; k < 2; ++k) \
;         acc[ai][bj][m][n] = __builtin_amdgcn_mfma_f32_16x16x32_bf16(Bt[n][k], At[m][k], acc[ai][bj][m][n], 0, 0, 0); __builtin_amdgcn_s_setprio(0); } while (0)
; #define PG8_WAIT_V(n) asm volatile("s_waitcnt vmcnt(" #n ")" ::: "memory")
; #define PG8_WAIT_L(n) asm volatile("s_waitcnt lgkmcnt(" #n ")" ::: "memory")
; #define PG8_BAR __builtin_amdgcn_s_barrier()
; #define PG8_SCHED __builtin_amdgcn_sched_barrier(0)
; template <class Epi, class Sched, bool ALIGN_EPI = false, bool SP2 = false>
; __device__ __forceinline__ void gemm_phase(PG8_LAS unsigned char* lds, const Gemm g, const Sched& S, const Epi& E) {
;     ...
;         for (int t = 0; t < nt; t += 2) {
;             const bool last = (t == nt - 2);
;     ...
;             PG8_LDA(At, 1, 1); PG8_STAGE(PG8_SB(1, 0), b3, voffB); PG8_STAGE(PG8_SB(1, 1), b3 + hstep, voffB); PG8_STAGE(PG8_SA(1, 0), a3, voffA);
;             PG8_WAIT_V(8); PG8_WAIT_L(0); PG8_BAR; PG8_MMA(1, 0, At, B0); PG8_MMA(1, 1, At, B1); PG8_BAR; PG8_SCHED;
	s_add_i32 s10, s10, s22
	v_lshl_add_u64 v[190:191], v[190:191], 0, s[36:37]
	s_mov_b32 m0, s10
	ds_read_b128 v[170:173], v185 offset:49152
	ds_read_b128 v[174:177], v185 offset:50176
	ds_read_b128 v[178:181], v185 offset:51200
	ds_read_b128 v[186:189], v185 offset:52224
	ds_read_b128 v[194:197], v185 offset:53248
	ds_read_b128 v[198:201], v185 offset:54272
	ds_read_b128 v[202:205], v185 offset:55296
	ds_read_b128 v[206:209], v185 offset:56320
	global_load_lds_dwordx4 v[190:191], off
	v_lshl_add_u64 v[190:191], v[210:211], 0, s[36:37]
	s_add_i32 m0, s10, 0x2000
	s_add_i32 s10, s11, s22
	global_load_lds_dwordx4 v[190:191], off
	v_lshl_add_u64 v[190:191], v[212:213], 0, s[36:37]
	s_mov_b32 m0, s10
	s_nop 0
	global_load_lds_dwordx4 v[190:191], off
	v_lshl_add_u64 v[190:191], v[214:215], 0, s[36:37]
	s_add_i32 m0, s10, 0x2000
	s_nop 0
	global_load_lds_dwordx4 v[190:191], off
	v_lshl_add_u64 v[190:191], v[216:217], 0, s[36:37]
	s_mov_b32 m0, s70
	s_nop 0
	global_load_lds_dwordx4 v[190:191], off
	v_lshl_add_u64 v[190:191], v[218:219], 0, s[36:37]
	s_mov_b32 m0, s71
	s_nop 0
	global_load_lds_dwordx4 v[190:191], off
	s_waitcnt vmcnt(8)
	s_waitcnt lgkmcnt(0)
	s_barrier
	s_setprio 1
	s_waitcnt lgkmcnt(0)
	v_mfma_f32_16x16x32_bf16 v[60:63], v[128:131], v[170:173], v[60:63]
	v_mfma_f32_16x16x32_bf16 v[56:59], v[136:139], v[170:173], v[56:59]
	v_mfma_f32_16x16x32_bf16 v[44:47], v[128:131], v[178:181], v[44:47]
	v_mfma_f32_16x16x32_bf16 v[40:43], v[136:139], v[178:181], v[40:43]
	v_mfma_f32_16x16x32_bf16 v[28:31], v[128:131], v[194:197], v[28:31]
	v_mfma_f32_16x16x32_bf16 v[24:27], v[136:139], v[194:197], v[24:27]
	v_mfma_f32_16x16x32_bf16 v[12:15], v[128:131], v[202:205], v[12:15]
	v_mfma_f32_16x16x32_bf16 v[8:11], v[136:139], v[202:205], v[8:11]
	v_mfma_f32_16x16x32_bf16 v[60:63], v[132:135], v[174:177], v[60:63]
	v_mfma_f32_16x16x32_bf16 v[56:59], v[140:143], v[174:177], v[56:59]
	v_mfma_f32_16x16x32_bf16 v[44:47], v[132:135], v[186:189], v[44:47]
	v_mfma_f32_16x16x32_bf16 v[40:43], v[140:143], v[186:189], v[40:43]
	v_mfma_f32_16x16x32_bf16 v[28:31], v[132:135], v[198:201], v[28:31]
	v_mfma_f32_16x16x32_bf16 v[24:27], v[140:143], v[198:201], v[24:27]
	v_mfma_f32_16x16x32_bf16 v[12:15], v[132:135], v[206:209], v[12:15]
	v_mfma_f32_16x16x32_bf16 v[8:11], v[140:143], v[206:209], v[8:11]
	s_setprio 0
	s_setprio 1
	v_mfma_f32_16x16x32_bf16 v[52:55], v[144:147], v[170:173], v[52:55]
	v_mfma_f32_16x16x32_bf16 v[48:51], v[152:155], v[170:173], v[48:51]
	v_mfma_f32_16x16x32_bf16 v[36:39], v[144:147], v[178:181], v[36:39]
	v_mfma_f32_16x16x32_bf16 v[32:35], v[152:155], v[178:181], v[32:35]
	v_mfma_f32_16x16x32_bf16 v[20:23], v[144:147], v[194:197], v[20:23]
	v_mfma_f32_16x16x32_bf16 v[16:19], v[152:155], v[194:197], v[16:19]
	v_mfma_f32_16x16x32_bf16 v[4:7], v[144:147], v[202:205], v[4:7]
	v_mfma_f32_16x16x32_bf16 v[0:3], v[152:155], v[202:205], v[0:3]
	v_mfma_f32_16x16x32_bf16 v[52:55], v[148:151], v[174:177], v[52:55]
	v_mfma_f32_16x16x32_bf16 v[48:51], v[166:169], v[174:177], v[48:51]
	v_mfma_f32_16x16x32_bf16 v[36:39], v[148:151], v[186:189], v[36:39]
	v_mfma_f32_16x16x32_bf16 v[32:35], v[166:169], v[186:189], v[32:35]
	v_mfma_f32_16x16x32_bf16 v[20:23], v[148:151], v[198:201], v[20:23]
	v_mfma_f32_16x16x32_bf16 v[16:19], v[166:169], v[198:201], v[16:19]
	v_mfma_f32_16x16x32_bf16 v[4:7], v[148:151], v[206:209], v[4:7]
	v_mfma_f32_16x16x32_bf16 v[0:3], v[166:169], v[206:209], v[0:3]
	s_setprio 0
	s_add_u32 s44, s44, 0x100
	s_addc_u32 s45, s45, 0
	s_add_u32 s19, s19, 0x100
	s_addc_u32 s20, s20, 0
	s_cmp_ge_u32 s66, s73
	s_mov_b32 s46, s66
	s_cbranch_scc1 .Llast_g1
	s_barrier
	s_branch .LBB0_63
.Llast_g1:
	s_and_b64 vcc, exec, s[56:57]
	s_cbranch_vccz .LBB0_66
	s_barrier

; #define PG8_STAGE(bufoff, gbase, voff) do { _Pragma("unroll") for (int _i = 0; _i < 2; ++_i) \
;         __builtin_amdgcn_global_load_lds((const unsigned*)((const char*)(gbase) + (voff)[_i]), (PG8_LAS unsigned*)(lds + (bufoff) + ldsw + _i * 8192), 16, 0, 0); } while (0)
; #define PG8_LDA(dst, b, h) do { _Pragma("unroll") for (int m = 0; m < 4; ++m) _Pragma("unroll") for (int k = 0; k < 2; ++k) dst[m][k] = *(const PG8_LAS bf16x8*)(lds + PG8_SA(b, h) + aoff + m * 2048 + k * 1024); } while (0)
; #define PG8_LDB(dst, b, h) do { _Pragma("unroll") for (int n = 0; n < 2; ++n) _Pragma("unroll") for (int k = 0; k < 2; ++k) dst[n][k] = *(const PG8_LAS bf16x8*)(lds + PG8_SB(b, h) + boff + n * 2048 + k * 1024); } while (0)
; #define PG8_MMA(ai, bj, At, Bt) do { __builtin_amdgcn_s_setprio(1); _Pragma("unroll") for (int m = 0; m < 4; ++m) _Pragma("unroll") for (int n = 0; n < 2; ++n) _Pragma("unroll") for (int k = 0; k < 2; ++k) \
;         acc[ai][bj][m][n] = __builtin_amdgcn_mfma_f32_16x16x32_bf16(Bt[n][k], At[m][k], acc[ai][bj][m][n], 0, 0, 0); __builtin_amdgcn_s_setprio(0); } while (0)
; #define PG8_WAIT_V(n) asm volatile("s_waitcnt vmcnt(" #n ")" ::: "memory")
; #define PG8_WAIT_L(n) asm volatile("s_waitcnt lgkmcnt(" #n ")" ::: "memory")
; template <class Epi, class Sched, bool ALIGN_EPI = false, bool SP2 = false>
; __device__ __forceinline__ void gemm_phase(PG8_LAS unsigned char* lds, const Gemm g, const Sched& S, const Epi& E) {
;     ...
;             const bool last = (t == nt - 2);
;             const char* a1 = cA + (size_t)(t + 1) * kstep;
;             const char* a2 = last ? nA : cA + (size_t)(t + 2) * kstep; const char* b2 = last ? nB : cB + (size_t)(t + 2) * kstep;
;             const char* a3 = a2 + kstep; const char* b3 = b2 + kstep;
;             if (last && has_next) S.a_ready(nxt);
;             if constexpr (SP2) {
;             PG8_LDB(B0, 0, 0); PG8_LDB(B1, 0, 1); PG8_SCHED; PG8_LDA(At, 0, 0); PG8_STAGE(PG8_SA(1, 1), a1 + hstep, voffA);
;             PG8_WAIT_V(8); PG8_WAIT_L(0); PG8_BAR; PG8_MMA(0, 0, At, B0); PG8_MMA(0, 1, At, B1); PG8_BAR; PG8_SCHED;
;             PG8_LDA(At, 0, 1); PG8_STAGE(PG8_SB(0, 0), b2, voffB); PG8_STAGE(PG8_SB(0, 1), b2 + hstep, voffB); PG8_STAGE(PG8_SA(0, 0), a2, voffA);
;             PG8_WAIT_V(8); PG8_WAIT_L(0); PG8_BAR; PG8_MMA(1, 0, At, B0); PG8_MMA(1, 1, At, B1); PG8_BAR; PG8_SCHED;
.LBB0_200:
	s_add_u32 s10, s56, 0xfffc0080
	s_addc_u32 s11, s57, -1
	s_add_i32 s77, 0, 0x10000
	s_cmp_eq_u32 s76, 12
	s_cselect_b32 s61, s18, s11
	s_cselect_b32 s60, s19, s10
	s_cselect_b32 s59, s20, s51
	s_cselect_b32 s58, s43, s49
	s_add_i32 s10, 0, 0x14000
	v_add_u32_e32 v140, s77, v163
	v_add_u32_e32 v162, s10, v163
	ds_read_b128 v[128:131], v140
	ds_read_b128 v[132:135], v140 offset:1024
	ds_read_b128 v[136:139], v140 offset:2048
	ds_read_b128 v[140:143], v140 offset:3072
	ds_read_b128 v[166:169], v162
	ds_read_b128 v[170:173], v162 offset:1024
	ds_read_b128 v[174:177], v162 offset:2048
	ds_read_b128 v[178:181], v162 offset:3072
	v_lshl_add_u64 v[190:191], s[56:57], 0, v[158:159]
	s_add_i32 m0, s64, 0xc000
	ds_read_b128 v[182:185], v165
	ds_read_b128 v[186:189], v165 offset:1024
	ds_read_b128 v[194:197], v165 offset:2048
	ds_read_b128 v[198:201], v165 offset:3072
	ds_read_b128 v[202:205], v165 offset:4096
	ds_read_b128 v[206:209], v165 offset:5120
	ds_read_b128 v[210:213], v165 offset:6144
	ds_read_b128 v[214:217], v165 offset:7168
	global_load_lds_dwordx4 v[190:191], off
	v_lshl_add_u64 v[190:191], s[56:57], 0, v[160:161]
	s_add_i32 m0, s64, 0xe000
	s_nop 0
	global_load_lds_dwordx4 v[190:191], off
	s_waitcnt vmcnt(8)
	s_waitcnt lgkmcnt(0)
	s_barrier
	s_setprio 1
	s_waitcnt lgkmcnt(0)
	v_mfma_f32_16x16x32_bf16 v[124:127], v[128:131], v[182:185], v[124:127]
	v_mfma_f32_16x16x32_bf16 v[120:123], v[136:139], v[182:185], v[120:123]
	v_mfma_f32_16x16x32_bf16 v[112:115], v[128:131], v[194:197], v[112:115]
	v_mfma_f32_16x16x32_bf16 v[104:107], v[136:139], v[194:197], v[104:107]
	v_mfma_f32_16x16x32_bf16 v[96:99], v[128:131], v[202:205], v[96:99]
	v_mfma_f32_16x16x32_bf16 v[88:91], v[136:139], v[202:205], v[88:91]
	v_mfma_f32_16x16x32_bf16 v[80:83], v[128:131], v[210:213], v[80:83]
	v_mfma_f32_16x16x32_bf16 v[72:75], v[136:139], v[210:213], v[72:75]
	v_mfma_f32_16x16x32_bf16 v[124:127], v[132:135], v[186:189], v[124:127]
	v_mfma_f32_16x16x32_bf16 v[120:123], v[140:143], v[186:189], v[120:123]
	v_mfma_f32_16x16x32_bf16 v[112:115], v[132:135], v[198:201], v[112:115]
	v_mfma_f32_16x16x32_bf16 v[104:107], v[140:143], v[198:201], v[104:107]
	v_mfma_f32_16x16x32_bf16 v[96:99], v[132:135], v[206:209], v[96:99]
	v_mfma_f32_16x16x32_bf16 v[88:91], v[140:143], v[206:209], v[88:91]
	v_mfma_f32_16x16x32_bf16 v[80:83], v[132:135], v[214:217], v[80:83]
	v_mfma_f32_16x16x32_bf16 v[72:75], v[140:143], v[214:217], v[72:75]
	s_setprio 0
	s_setprio 1
	v_mfma_f32_16x16x32_bf16 v[116:119], v[166:169], v[182:185], v[116:119]
	v_mfma_f32_16x16x32_bf16 v[108:111], v[174:177], v[182:185], v[108:111]
	v_mfma_f32_16x16x32_bf16 v[100:103], v[166:169], v[194:197], v[100:103]
	v_mfma_f32_16x16x32_bf16 v[92:95], v[174:177], v[194:197], v[92:95]
	v_mfma_f32_16x16x32_bf16 v[84:87], v[166:169], v[202:205], v[84:87]
	v_mfma_f32_16x16x32_bf16 v[76:79], v[174:177], v[202:205], v[76:79]
	v_mfma_f32_16x16x32_bf16 v[68:71], v[166:169], v[210:213], v[68:71]
	v_mfma_f32_16x16x32_bf16 v[64:67], v[174:177], v[210:213], v[64:67]
	v_mfma_f32_16x16x32_bf16 v[116:119], v[170:173], v[186:189], v[116:119]
	v_mfma_f32_16x16x32_bf16 v[108:111], v[178:181], v[186:189], v[108:111]
	v_mfma_f32_16x16x32_bf16 v[100:103], v[170:173], v[198:201], v[100:103]
	v_mfma_f32_16x16x32_bf16 v[92:95], v[178:181], v[198:201], v[92:95]
	v_mfma_f32_16x16x32_bf16 v[84:87], v[170:173], v[206:209], v[84:87]
	v_mfma_f32_16x16x32_bf16 v[76:79], v[178:181], v[206:209], v[76:79]
	v_mfma_f32_16x16x32_bf16 v[68:71], v[170:173], v[214:217], v[68:71]
	v_mfma_f32_16x16x32_bf16 v[64:67], v[178:181], v[214:217], v[64:67]
	s_setprio 0
	s_barrier
	s_add_i32 s11, s77, s63
	v_lshl_add_u64 v[190:191], s[58:59], 0, v[146:147]
	s_mov_b32 m0, s11
	ds_read_b128 v[182:185], v165 offset:16384
	ds_read_b128 v[186:189], v165 offset:17408
	ds_read_b128 v[194:197], v165 offset:18432
	ds_read_b128 v[198:201], v165 offset:19456
	ds_read_b128 v[202:205], v165 offset:20480
	ds_read_b128 v[206:209], v165 offset:21504
	ds_read_b128 v[210:213], v165 offset:22528
	ds_read_b128 v[214:217], v165 offset:23552
	global_load_lds_dwordx4 v[190:191], off
	s_add_i32 m0, s11, 0x2000
	s_add_u32 s78, s58, 0x40000
	v_lshl_add_u64 v[218:219], s[58:59], 0, v[150:151]
	s_addc_u32 s79, s59, 0
	s_add_i32 s10, s10, s63
	global_load_lds_dwordx4 v[218:219], off
	v_lshl_add_u64 v[220:221], s[78:79], 0, v[146:147]
	s_mov_b32 m0, s10
	v_lshl_add_u64 v[222:223], s[60:61], 0, v[148:149]
	global_load_lds_dwordx4 v[220:221], off
	v_lshl_add_u64 v[220:221], s[78:79], 0, v[150:151]
	s_add_i32 m0, s10, 0x2000
	s_nop 0
	global_load_lds_dwordx4 v[220:221], off
	v_lshl_add_u64 v[220:221], s[60:61], 0, v[144:145]
	s_mov_b32 m0, s64
	s_nop 0
	global_load_lds_dwordx4 v[220:221], off
	s_mov_b32 m0, s65
	s_nop 0
	global_load_lds_dwordx4 v[222:223], off
	s_waitcnt vmcnt(8)
	s_waitcnt lgkmcnt(0)
	s_barrier
; #define PG8_STAGE(bufoff, gbase, voff) do { _Pragma("unroll") for (int _i = 0; _i < 2; ++_i) \
;         __builtin_amdgcn_global_load_lds((const unsigned*)((const char*)(gbase) + (voff)[_i]), (PG8_LAS unsigned*)(lds + (bufoff) + ldsw + _i * 8192), 16, 0, 0); } while (0)
; #define PG8_LDA(dst, b, h) do { _Pragma("unroll") for (int m = 0; m < 4; ++m) _Pragma("unroll") for (int k = 0; k < 2; ++k) dst[m][k] = *(const PG8_LAS bf16x8*)(lds + PG8_SA(b, h) + aoff + m * 2048 + k * 1024); } while (0)
; #define PG8_LDB(dst, b, h) do { _Pragma("unroll") for (int n = 0; n < 2; ++n) _Pragma("unroll") for (int k = 0; k < 2; ++k) dst[n][k] = *(const PG8_LAS bf16x8*)(lds + PG8_SB(b, h) + boff + n * 2048 + k * 1024); } while (0)
; #define PG8_MMA(ai, bj, At, Bt) do { __builtin_amdgcn_s_setprio(1); _Pragma("unroll") for (int m = 0; m < 4; ++m) _Pragma("unroll") for (int n = 0; n < 2; ++n) _Pragma("unroll") for (int k = 0; k < 2; ++k) \
;         acc[ai][bj][m][n] = __builtin_amdgcn_mfma_f32_16x16x32_bf16(Bt[n][k], At[m][k], acc[ai][bj][m][n], 0, 0, 0); __builtin_amdgcn_s_setprio(0); } while (0)
; #define PG8_WAIT_V(n) asm volatile("s_waitcnt vmcnt(" #n ")" ::: "memory")
; #define PG8_WAIT_L(n) asm volatile("s_waitcnt lgkmcnt(" #n ")" ::: "memory")
; #define PG8_BAR __builtin_amdgcn_s_barrier()
; #define PG8_SCHED __builtin_amdgcn_sched_barrier(0)
; template <class Epi, class Sched, bool ALIGN_EPI = false, bool SP2 = false>
; __device__ __forceinline__ void gemm_phase(PG8_LAS unsigned char* lds, const Gemm g, const Sched& S, const Epi& E) {
;     ...
;             PG8_WAIT_V(8); PG8_WAIT_L(0); PG8_BAR; PG8_MMA(1, 0, At, B0); PG8_MMA(1, 1, At, B1); PG8_BAR; PG8_SCHED;
;             PG8_LDB(B0, 1, 0); PG8_LDB(B1, 1, 1); PG8_SCHED; PG8_LDA(At, 1, 0); PG8_STAGE(PG8_SA(0, 1), a2 + hstep, voffA);
;             PG8_WAIT_V(8); PG8_WAIT_L(0); PG8_BAR; PG8_MMA(0, 0, At, B0); PG8_MMA(0, 1, At, B1); PG8_BAR; PG8_SCHED;
	s_setprio 1
	s_waitcnt lgkmcnt(0)
	v_mfma_f32_16x16x32_bf16 v[60:63], v[128:131], v[182:185], v[60:63]
	v_mfma_f32_16x16x32_bf16 v[56:59], v[136:139], v[182:185], v[56:59]
	v_mfma_f32_16x16x32_bf16 v[48:51], v[128:131], v[194:197], v[48:51]
	v_mfma_f32_16x16x32_bf16 v[40:43], v[136:139], v[194:197], v[40:43]
	v_mfma_f32_16x16x32_bf16 v[32:35], v[128:131], v[202:205], v[32:35]
	v_mfma_f32_16x16x32_bf16 v[24:27], v[136:139], v[202:205], v[24:27]
	v_mfma_f32_16x16x32_bf16 v[16:19], v[128:131], v[210:213], v[16:19]
	v_mfma_f32_16x16x32_bf16 v[8:11], v[136:139], v[210:213], v[8:11]
	v_mfma_f32_16x16x32_bf16 v[60:63], v[132:135], v[186:189], v[60:63]
	v_mfma_f32_16x16x32_bf16 v[56:59], v[140:143], v[186:189], v[56:59]
	v_mfma_f32_16x16x32_bf16 v[48:51], v[132:135], v[198:201], v[48:51]
	v_mfma_f32_16x16x32_bf16 v[40:43], v[140:143], v[198:201], v[40:43]
	v_mfma_f32_16x16x32_bf16 v[32:35], v[132:135], v[206:209], v[32:35]
	v_mfma_f32_16x16x32_bf16 v[24:27], v[140:143], v[206:209], v[24:27]
	v_mfma_f32_16x16x32_bf16 v[16:19], v[132:135], v[214:217], v[16:19]
	v_mfma_f32_16x16x32_bf16 v[8:11], v[140:143], v[214:217], v[8:11]
	s_setprio 0
	s_setprio 1
	v_mfma_f32_16x16x32_bf16 v[52:55], v[166:169], v[182:185], v[52:55]
	v_mfma_f32_16x16x32_bf16 v[44:47], v[174:177], v[182:185], v[44:47]
	v_mfma_f32_16x16x32_bf16 v[36:39], v[166:169], v[194:197], v[36:39]
	v_mfma_f32_16x16x32_bf16 v[28:31], v[174:177], v[194:197], v[28:31]
	v_mfma_f32_16x16x32_bf16 v[20:23], v[166:169], v[202:205], v[20:23]
	v_mfma_f32_16x16x32_bf16 v[12:15], v[174:177], v[202:205], v[12:15]
	v_mfma_f32_16x16x32_bf16 v[4:7], v[166:169], v[210:213], v[4:7]
	v_mfma_f32_16x16x32_bf16 v[0:3], v[174:177], v[210:213], v[0:3]
	v_mfma_f32_16x16x32_bf16 v[52:55], v[170:173], v[186:189], v[52:55]
	v_mfma_f32_16x16x32_bf16 v[44:47], v[178:181], v[186:189], v[44:47]
	v_mfma_f32_16x16x32_bf16 v[36:39], v[170:173], v[198:201], v[36:39]
	v_mfma_f32_16x16x32_bf16 v[28:31], v[178:181], v[198:201], v[28:31]
	v_mfma_f32_16x16x32_bf16 v[20:23], v[170:173], v[206:209], v[20:23]
	v_mfma_f32_16x16x32_bf16 v[12:15], v[178:181], v[206:209], v[12:15]
	v_mfma_f32_16x16x32_bf16 v[4:7], v[170:173], v[214:217], v[4:7]
	v_mfma_f32_16x16x32_bf16 v[0:3], v[178:181], v[214:217], v[0:3]
	s_setprio 0
	s_barrier
	s_add_i32 s10, 0, 0x18000
	s_add_i32 s11, 0, 0x1c000
	v_add_u32_e32 v140, s10, v163
	v_add_u32_e32 v162, s11, v163
	ds_read_b128 v[128:131], v140
	ds_read_b128 v[132:135], v140 offset:1024
	ds_read_b128 v[136:139], v140 offset:2048
	ds_read_b128 v[140:143], v140 offset:3072
	ds_read_b128 v[166:169], v162
	ds_read_b128 v[170:173], v162 offset:1024
	ds_read_b128 v[174:177], v162 offset:2048
	ds_read_b128 v[178:181], v162 offset:3072
	s_add_u32 s60, s60, 0x40000
	s_addc_u32 s61, s61, 0
	s_mov_b32 m0, s66
	v_lshl_add_u64 v[224:225], s[60:61], 0, v[144:145]
	ds_read_b128 v[182:185], v165 offset:32768
	ds_read_b128 v[186:189], v165 offset:33792
	ds_read_b128 v[194:197], v165 offset:34816
	ds_read_b128 v[198:201], v165 offset:35840
	ds_read_b128 v[202:205], v165 offset:36864
	ds_read_b128 v[206:209], v165 offset:37888
	ds_read_b128 v[210:213], v165 offset:38912
	ds_read_b128 v[214:217], v165 offset:39936
	global_load_lds_dwordx4 v[224:225], off
	v_lshl_add_u64 v[224:225], s[60:61], 0, v[148:149]
	s_mov_b32 m0, s67
	s_nop 0
	global_load_lds_dwordx4 v[224:225], off
	s_waitcnt vmcnt(8)
	s_waitcnt lgkmcnt(0)
	s_barrier
	s_setprio 1
	s_waitcnt lgkmcnt(0)
	v_mfma_f32_16x16x32_bf16 v[124:127], v[128:131], v[182:185], v[124:127]
	v_mfma_f32_16x16x32_bf16 v[120:123], v[136:139], v[182:185], v[120:123]
	v_mfma_f32_16x16x32_bf16 v[112:115], v[128:131], v[194:197], v[112:115]
	v_mfma_f32_16x16x32_bf16 v[104:107], v[136:139], v[194:197], v[104:107]
	v_mfma_f32_16x16x32_bf16 v[96:99], v[128:131], v[202:205], v[96:99]
	v_mfma_f32_16x16x32_bf16 v[88:91], v[136:139], v[202:205], v[88:91]
	v_mfma_f32_16x16x32_bf16 v[80:83], v[128:131], v[210:213], v[80:83]
	v_mfma_f32_16x16x32_bf16 v[72:75], v[136:139], v[210:213], v[72:75]
	v_mfma_f32_16x16x32_bf16 v[124:127], v[132:135], v[186:189], v[124:127]
	v_mfma_f32_16x16x32_bf16 v[120:123], v[140:143], v[186:189], v[120:123]
	v_mfma_f32_16x16x32_bf16 v[112:115], v[132:135], v[198:201], v[112:115]
	v_mfma_f32_16x16x32_bf16 v[104:107], v[140:143], v[198:201], v[104:107]
	v_mfma_f32_16x16x32_bf16 v[96:99], v[132:135], v[206:209], v[96:99]
	v_mfma_f32_16x16x32_bf16 v[88:91], v[140:143], v[206:209], v[88:91]
	v_mfma_f32_16x16x32_bf16 v[80:83], v[132:135], v[214:217], v[80:83]
	v_mfma_f32_16x16x32_bf16 v[72:75], v[140:143], v[214:217], v[72:75]
	s_setprio 0
	s_setprio 1
	v_mfma_f32_16x16x32_bf16 v[116:119], v[166:169], v[182:185], v[116:119]
	v_mfma_f32_16x16x32_bf16 v[108:111], v[174:177], v[182:185], v[108:111]
	v_mfma_f32_16x16x32_bf16 v[100:103], v[166:169], v[194:197], v[100:103]
	v_mfma_f32_16x16x32_bf16 v[92:95], v[174:177], v[194:197], v[92:95]
	v_mfma_f32_16x16x32_bf16 v[84:87], v[166:169], v[202:205], v[84:87]
	v_mfma_f32_16x16x32_bf16 v[76:79], v[174:177], v[202:205], v[76:79]
	v_mfma_f32_16x16x32_bf16 v[68:71], v[166:169], v[210:213], v[68:71]
	v_mfma_f32_16x16x32_bf16 v[64:67], v[174:177], v[210:213], v[64:67]
	v_mfma_f32_16x16x32_bf16 v[116:119], v[170:173], v[186:189], v[116:119]
	v_mfma_f32_16x16x32_bf16 v[108:111], v[178:181], v[186:189], v[108:111]
	v_mfma_f32_16x16x32_bf16 v[100:103], v[170:173], v[198:201], v[100:103]
	v_mfma_f32_16x16x32_bf16 v[92:95], v[178:181], v[198:201], v[92:95]
	v_mfma_f32_16x16x32_bf16 v[84:87], v[170:173], v[206:209], v[84:87]
	v_mfma_f32_16x16x32_bf16 v[76:79], v[178:181], v[206:209], v[76:79]
	v_mfma_f32_16x16x32_bf16 v[68:71], v[170:173], v[214:217], v[68:71]
	v_mfma_f32_16x16x32_bf16 v[64:67], v[178:181], v[214:217], v[64:67]
	s_setprio 0
	s_barrier
; #define PG8_STAGE(bufoff, gbase, voff) do { _Pragma("unroll") for (int _i = 0; _i < 2; ++_i) \
;         __builtin_amdgcn_global_load_lds((const unsigned*)((const char*)(gbase) + (voff)[_i]), (PG8_LAS unsigned*)(lds + (bufoff) + ldsw + _i * 8192), 16, 0, 0); } while (0)
; #define PG8_LDA(dst, b, h) do { _Pragma("unroll") for (int m = 0; m < 4; ++m) _Pragma("unroll") for (int k = 0; k < 2; ++k) dst[m][k] = *(const PG8_LAS bf16x8*)(lds + PG8_SA(b, h) + aoff + m * 2048 + k * 1024); } while (0)
; #define PG8_MMA(ai, bj, At, Bt) do { __builtin_amdgcn_s_setprio(1); _Pragma("unroll") for (int m = 0; m < 4; ++m) _Pragma("unroll") for (int n = 0; n < 2; ++n) _Pragma("unroll") for (int k = 0; k < 2; ++k) \
;         acc[ai][bj][m][n] = __builtin_amdgcn_mfma_f32_16x16x32_bf16(Bt[n][k], At[m][k], acc[ai][bj][m][n], 0, 0, 0); __builtin_amdgcn_s_setprio(0); } while (0)
; #define PG8_WAIT_V(n) asm volatile("s_waitcnt vmcnt(" #n ")" ::: "memory")
; #define PG8_WAIT_L(n) asm volatile("s_waitcnt lgkmcnt(" #n ")" ::: "memory")
; #define PG8_BAR __builtin_amdgcn_s_barrier()
; #define PG8_SCHED __builtin_amdgcn_sched_barrier(0)
; template <class Epi, class Sched, bool ALIGN_EPI = false, bool SP2 = false>
; __device__ __forceinline__ void gemm_phase(PG8_LAS unsigned char* lds, const Gemm g, const Sched& S, const Epi& E) {
;     ...
;         for (int t = 0; t < nt; t += 2) {
;             const bool last = (t == nt - 2);
;     ...
;             PG8_LDA(At, 1, 1); PG8_STAGE(PG8_SB(1, 0), b3, voffB); PG8_STAGE(PG8_SB(1, 1), b3 + hstep, voffB); PG8_STAGE(PG8_SA(1, 0), a3, voffA);
;             PG8_WAIT_V(8); PG8_WAIT_L(0); PG8_BAR; PG8_MMA(1, 0, At, B0); PG8_MMA(1, 1, At, B1); PG8_BAR; PG8_SCHED;
	s_add_i32 s10, s10, s63
	v_lshl_add_u64 v[190:191], v[190:191], 0, s[36:37]
	s_mov_b32 m0, s10
	ds_read_b128 v[182:185], v165 offset:49152
	ds_read_b128 v[186:189], v165 offset:50176
	ds_read_b128 v[194:197], v165 offset:51200
	ds_read_b128 v[198:201], v165 offset:52224
	ds_read_b128 v[202:205], v165 offset:53248
	ds_read_b128 v[206:209], v165 offset:54272
	ds_read_b128 v[210:213], v165 offset:55296
	ds_read_b128 v[214:217], v165 offset:56320
	global_load_lds_dwordx4 v[190:191], off
	s_add_i32 m0, s10, 0x2000
	s_add_u32 s58, s58, 0x40080
	v_lshl_add_u64 v[190:191], v[218:219], 0, s[36:37]
	s_addc_u32 s59, s59, 0
	s_add_i32 s10, s11, s63
	global_load_lds_dwordx4 v[190:191], off
	v_lshl_add_u64 v[190:191], s[58:59], 0, v[146:147]
	s_mov_b32 m0, s10
	s_nop 0
	global_load_lds_dwordx4 v[190:191], off
	v_lshl_add_u64 v[190:191], s[58:59], 0, v[150:151]
	s_add_i32 m0, s10, 0x2000
	s_nop 0
	global_load_lds_dwordx4 v[190:191], off
	v_lshl_add_u64 v[190:191], v[220:221], 0, s[36:37]
	s_mov_b32 m0, s70
	s_nop 0
	global_load_lds_dwordx4 v[190:191], off
	v_lshl_add_u64 v[190:191], v[222:223], 0, s[36:37]
	s_mov_b32 m0, s71
	s_nop 0
	global_load_lds_dwordx4 v[190:191], off
	s_waitcnt vmcnt(8)
	s_waitcnt lgkmcnt(0)
	s_barrier
	s_setprio 1
	s_waitcnt lgkmcnt(0)
	v_mfma_f32_16x16x32_bf16 v[60:63], v[128:131], v[182:185], v[60:63]
	v_mfma_f32_16x16x32_bf16 v[56:59], v[136:139], v[182:185], v[56:59]
	v_mfma_f32_16x16x32_bf16 v[48:51], v[128:131], v[194:197], v[48:51]
	v_mfma_f32_16x16x32_bf16 v[40:43], v[136:139], v[194:197], v[40:43]
	v_mfma_f32_16x16x32_bf16 v[32:35], v[128:131], v[202:205], v[32:35]
	v_mfma_f32_16x16x32_bf16 v[24:27], v[136:139], v[202:205], v[24:27]
	v_mfma_f32_16x16x32_bf16 v[16:19], v[128:131], v[210:213], v[16:19]
	v_mfma_f32_16x16x32_bf16 v[8:11], v[136:139], v[210:213], v[8:11]
	v_mfma_f32_16x16x32_bf16 v[60:63], v[132:135], v[186:189], v[60:63]
	v_mfma_f32_16x16x32_bf16 v[56:59], v[140:143], v[186:189], v[56:59]
	v_mfma_f32_16x16x32_bf16 v[48:51], v[132:135], v[198:201], v[48:51]
	v_mfma_f32_16x16x32_bf16 v[40:43], v[140:143], v[198:201], v[40:43]
	v_mfma_f32_16x16x32_bf16 v[32:35], v[132:135], v[206:209], v[32:35]
	v_mfma_f32_16x16x32_bf16 v[24:27], v[140:143], v[206:209], v[24:27]
	v_mfma_f32_16x16x32_bf16 v[16:19], v[132:135], v[214:217], v[16:19]
	v_mfma_f32_16x16x32_bf16 v[8:11], v[140:143], v[214:217], v[8:11]
	s_setprio 0
	s_setprio 1
	v_mfma_f32_16x16x32_bf16 v[52:55], v[166:169], v[182:185], v[52:55]
	v_mfma_f32_16x16x32_bf16 v[44:47], v[174:177], v[182:185], v[44:47]
	v_mfma_f32_16x16x32_bf16 v[36:39], v[166:169], v[194:197], v[36:39]
	v_mfma_f32_16x16x32_bf16 v[28:31], v[174:177], v[194:197], v[28:31]
	v_mfma_f32_16x16x32_bf16 v[20:23], v[166:169], v[202:205], v[20:23]
	v_mfma_f32_16x16x32_bf16 v[12:15], v[174:177], v[202:205], v[12:15]
	v_mfma_f32_16x16x32_bf16 v[4:7], v[166:169], v[210:213], v[4:7]
	v_mfma_f32_16x16x32_bf16 v[0:3], v[174:177], v[210:213], v[0:3]
	v_mfma_f32_16x16x32_bf16 v[52:55], v[170:173], v[186:189], v[52:55]
	v_mfma_f32_16x16x32_bf16 v[44:47], v[178:181], v[186:189], v[44:47]
	v_mfma_f32_16x16x32_bf16 v[36:39], v[170:173], v[198:201], v[36:39]
	v_mfma_f32_16x16x32_bf16 v[28:31], v[178:181], v[198:201], v[28:31]
	v_mfma_f32_16x16x32_bf16 v[20:23], v[170:173], v[206:209], v[20:23]
	v_mfma_f32_16x16x32_bf16 v[12:15], v[178:181], v[206:209], v[12:15]
	v_mfma_f32_16x16x32_bf16 v[4:7], v[170:173], v[214:217], v[4:7]
	v_mfma_f32_16x16x32_bf16 v[0:3], v[178:181], v[214:217], v[0:3]
	s_setprio 0
	s_add_i32 s76, s76, 2
	s_add_u32 s56, s56, 0x100
	s_addc_u32 s57, s57, 0
	s_add_u32 s49, s49, 0x100
	s_addc_u32 s51, s51, 0
	s_cmp_gt_u32 s76, 13
	s_cbranch_scc1 .Llast_g2
	s_barrier
	s_branch .LBB0_200
.Llast_g2:
	s_and_b64 vcc, exec, s[44:45]
	s_cbranch_vccz .LBB0_203
	s_barrier

; #define PG8_STAGE(bufoff, gbase, voff) do { _Pragma("unroll") for (int _i = 0; _i < 2; ++_i) \
;         __builtin_amdgcn_global_load_lds((const unsigned*)((const char*)(gbase) + (voff)[_i]), (PG8_LAS unsigned*)(lds + (bufoff) + ldsw + _i * 8192), 16, 0, 0); } while (0)
; #define PG8_LDA(dst, b, h) do { _Pragma("unroll") for (int m = 0; m < 4; ++m) _Pragma("unroll") for (int k = 0; k < 2; ++k) dst[m][k] = *(const PG8_LAS bf16x8*)(lds + PG8_SA(b, h) + aoff + m * 2048 + k * 1024); } while (0)
; #define PG8_LDB(dst, b, h) do { _Pragma("unroll") for (int n = 0; n < 2; ++n) _Pragma("unroll") for (int k = 0; k < 2; ++k) dst[n][k] = *(const PG8_LAS bf16x8*)(lds + PG8_SB(b, h) + boff + n * 2048 + k * 1024); } while (0)
; #define PG8_MMA(ai, bj, At, Bt) do { __builtin_amdgcn_s_setprio(1); _Pragma("unroll") for (int m = 0; m < 4; ++m) _Pragma("unroll") for (int n = 0; n < 2; ++n) _Pragma("unroll") for (int k = 0; k < 2; ++k) \
;         acc[ai][bj][m][n] = __builtin_amdgcn_mfma_f32_16x16x32_bf16(Bt[n][k], At[m][k], acc[ai][bj][m][n], 0, 0, 0); __builtin_amdgcn_s_setprio(0); } while (0)
; #define PG8_WAIT_V(n) asm volatile("s_waitcnt vmcnt(" #n ")" ::: "memory")
; #define PG8_WAIT_L(n) asm volatile("s_waitcnt lgkmcnt(" #n ")" ::: "memory")
; template <class Epi, class Sched, bool ALIGN_EPI = false, bool SP2 = false>
; __device__ __forceinline__ void gemm_phase(PG8_LAS unsigned char* lds, const Gemm g, const Sched& S, const Epi& E) {
;     ...
;             const bool last = (t == nt - 2);
;             const char* a1 = cA + (size_t)(t + 1) * kstep;
;             const char* a2 = last ? nA : cA + (size_t)(t + 2) * kstep; const char* b2 = last ? nB : cB + (size_t)(t + 2) * kstep;
;             const char* a3 = a2 + kstep; const char* b3 = b2 + kstep;
;             if (last && has_next) S.a_ready(nxt);
;             if constexpr (SP2) {
;             PG8_LDB(B0, 0, 0); PG8_LDB(B1, 0, 1); PG8_SCHED; PG8_LDA(At, 0, 0); PG8_STAGE(PG8_SA(1, 1), a1 + hstep, voffA);
;             PG8_WAIT_V(8); PG8_WAIT_L(0); PG8_BAR; PG8_MMA(0, 0, At, B0); PG8_MMA(0, 1, At, B1); PG8_BAR; PG8_SCHED;
;             PG8_LDA(At, 0, 1); PG8_STAGE(PG8_SB(0, 0), b2, voffB); PG8_STAGE(PG8_SB(0, 1), b2 + hstep, voffB); PG8_STAGE(PG8_SA(0, 0), a2, voffA);
;             PG8_WAIT_V(8); PG8_WAIT_L(0); PG8_BAR; PG8_MMA(1, 0, At, B0); PG8_MMA(1, 1, At, B1); PG8_BAR; PG8_SCHED;
.LBB0_488:
	s_add_u32 s10, s34, 0xfffc0080
	s_addc_u32 s11, s35, -1
	s_add_i32 s77, 0, 0x10000
	s_cmp_eq_u32 s76, 4
	s_cselect_b32 s53, s45, s11
	s_cselect_b32 s52, s44, s10
	s_cselect_b32 s51, s49, s75
	s_cselect_b32 s50, s48, s19
	s_add_i32 s78, 0, 0x14000
	v_add_u32_e32 v140, s77, v246
	v_add_u32_e32 v156, s78, v246
	ds_read_b128 v[128:131], v140
	ds_read_b128 v[132:135], v140 offset:1024
	ds_read_b128 v[136:139], v140 offset:2048
	ds_read_b128 v[140:143], v140 offset:3072
	ds_read_b128 v[144:147], v156
	ds_read_b128 v[148:151], v156 offset:1024
	ds_read_b128 v[152:155], v156 offset:2048
	ds_read_b128 v[156:159], v156 offset:3072
	v_lshl_add_u64 v[208:209], s[34:35], 0, v[204:205]
	s_add_i32 m0, s55, 0xc000
	ds_read_b128 v[160:163], v249
	ds_read_b128 v[164:167], v249 offset:1024
	ds_read_b128 v[168:171], v249 offset:2048
	ds_read_b128 v[172:175], v249 offset:3072
	ds_read_b128 v[176:179], v249 offset:4096
	ds_read_b128 v[180:183], v249 offset:5120
	ds_read_b128 v[184:187], v249 offset:6144
	ds_read_b128 v[188:191], v249 offset:7168
	global_load_lds_dwordx4 v[208:209], off
	v_lshl_add_u64 v[208:209], s[34:35], 0, v[206:207]
	s_add_i32 m0, s55, 0xe000
	s_nop 0
	global_load_lds_dwordx4 v[208:209], off
	s_waitcnt vmcnt(8)
	s_waitcnt lgkmcnt(0)
	s_barrier
	s_setprio 1
	s_waitcnt lgkmcnt(0)
	v_mfma_f32_16x16x32_bf16 v[124:127], v[128:131], v[160:163], v[124:127]
	v_mfma_f32_16x16x32_bf16 v[120:123], v[136:139], v[160:163], v[120:123]
	v_mfma_f32_16x16x32_bf16 v[116:119], v[128:131], v[168:171], v[116:119]
	v_mfma_f32_16x16x32_bf16 v[112:115], v[136:139], v[168:171], v[112:115]
	v_mfma_f32_16x16x32_bf16 v[108:111], v[128:131], v[176:179], v[108:111]
	v_mfma_f32_16x16x32_bf16 v[104:107], v[136:139], v[176:179], v[104:107]
	v_mfma_f32_16x16x32_bf16 v[100:103], v[128:131], v[184:187], v[100:103]
	v_mfma_f32_16x16x32_bf16 v[96:99], v[136:139], v[184:187], v[96:99]
	v_mfma_f32_16x16x32_bf16 v[124:127], v[132:135], v[164:167], v[124:127]
	v_mfma_f32_16x16x32_bf16 v[120:123], v[140:143], v[164:167], v[120:123]
	v_mfma_f32_16x16x32_bf16 v[116:119], v[132:135], v[172:175], v[116:119]
	v_mfma_f32_16x16x32_bf16 v[112:115], v[140:143], v[172:175], v[112:115]
	v_mfma_f32_16x16x32_bf16 v[108:111], v[132:135], v[180:183], v[108:111]
	v_mfma_f32_16x16x32_bf16 v[104:107], v[140:143], v[180:183], v[104:107]
	v_mfma_f32_16x16x32_bf16 v[100:103], v[132:135], v[188:191], v[100:103]
	v_mfma_f32_16x16x32_bf16 v[96:99], v[140:143], v[188:191], v[96:99]
	s_setprio 0
	s_setprio 1
	v_mfma_f32_16x16x32_bf16 v[92:95], v[144:147], v[160:163], v[92:95]
	v_mfma_f32_16x16x32_bf16 v[88:91], v[152:155], v[160:163], v[88:91]
	v_mfma_f32_16x16x32_bf16 v[84:87], v[144:147], v[168:171], v[84:87]
	v_mfma_f32_16x16x32_bf16 v[80:83], v[152:155], v[168:171], v[80:83]
	v_mfma_f32_16x16x32_bf16 v[76:79], v[144:147], v[176:179], v[76:79]
	v_mfma_f32_16x16x32_bf16 v[72:75], v[152:155], v[176:179], v[72:75]
	v_mfma_f32_16x16x32_bf16 v[68:71], v[144:147], v[184:187], v[68:71]
	v_mfma_f32_16x16x32_bf16 v[64:67], v[152:155], v[184:187], v[64:67]
	v_mfma_f32_16x16x32_bf16 v[92:95], v[148:151], v[164:167], v[92:95]
	v_mfma_f32_16x16x32_bf16 v[88:91], v[156:159], v[164:167], v[88:91]
	v_mfma_f32_16x16x32_bf16 v[84:87], v[148:151], v[172:175], v[84:87]
	v_mfma_f32_16x16x32_bf16 v[80:83], v[156:159], v[172:175], v[80:83]
	v_mfma_f32_16x16x32_bf16 v[76:79], v[148:151], v[180:183], v[76:79]
	v_mfma_f32_16x16x32_bf16 v[72:75], v[156:159], v[180:183], v[72:75]
	v_mfma_f32_16x16x32_bf16 v[68:71], v[148:151], v[188:191], v[68:71]
	v_mfma_f32_16x16x32_bf16 v[64:67], v[156:159], v[188:191], v[64:67]
	s_setprio 0
	s_barrier
	s_add_i32 s10, s77, s14
	v_lshl_add_u64 v[208:209], s[50:51], 0, v[198:199]
	s_mov_b32 m0, s10
	ds_read_b128 v[160:163], v249 offset:16384
	ds_read_b128 v[164:167], v249 offset:17408
	ds_read_b128 v[168:171], v249 offset:18432
	ds_read_b128 v[172:175], v249 offset:19456
	ds_read_b128 v[176:179], v249 offset:20480
	ds_read_b128 v[180:183], v249 offset:21504
	ds_read_b128 v[184:187], v249 offset:22528
	ds_read_b128 v[188:191], v249 offset:23552
	global_load_lds_dwordx4 v[208:209], off
	s_add_i32 m0, s10, 0x2000
	s_add_u32 s10, s50, 0x40000
	v_lshl_add_u64 v[210:211], s[50:51], 0, v[194:195]
	s_addc_u32 s11, s51, 0
	s_add_i32 s77, s78, s14
	global_load_lds_dwordx4 v[210:211], off
	v_lshl_add_u64 v[212:213], s[10:11], 0, v[198:199]
	s_mov_b32 m0, s77
	v_lshl_add_u64 v[214:215], s[52:53], 0, v[196:197]
	global_load_lds_dwordx4 v[212:213], off
	v_lshl_add_u64 v[212:213], s[10:11], 0, v[194:195]
	s_add_i32 m0, s77, 0x2000
	s_nop 0
	global_load_lds_dwordx4 v[212:213], off
	v_lshl_add_u64 v[212:213], s[52:53], 0, v[200:201]
	s_mov_b32 m0, s55
	s_nop 0
	global_load_lds_dwordx4 v[212:213], off
	s_mov_b32 m0, s58
	s_nop 0
	global_load_lds_dwordx4 v[214:215], off
	s_waitcnt vmcnt(8)
	s_waitcnt lgkmcnt(0)
	s_barrier
; #define PG8_STAGE(bufoff, gbase, voff) do { _Pragma("unroll") for (int _i = 0; _i < 2; ++_i) \
;         __builtin_amdgcn_global_load_lds((const unsigned*)((const char*)(gbase) + (voff)[_i]), (PG8_LAS unsigned*)(lds + (bufoff) + ldsw + _i * 8192), 16, 0, 0); } while (0)
; #define PG8_LDA(dst, b, h) do { _Pragma("unroll") for (int m = 0; m < 4; ++m) _Pragma("unroll") for (int k = 0; k < 2; ++k) dst[m][k] = *(const PG8_LAS bf16x8*)(lds + PG8_SA(b, h) + aoff + m * 2048 + k * 1024); } while (0)
; #define PG8_LDB(dst, b, h) do { _Pragma("unroll") for (int n = 0; n < 2; ++n) _Pragma("unroll") for (int k = 0; k < 2; ++k) dst[n][k] = *(const PG8_LAS bf16x8*)(lds + PG8_SB(b, h) + boff + n * 2048 + k * 1024); } while (0)
; #define PG8_MMA(ai, bj, At, Bt) do { __builtin_amdgcn_s_setprio(1); _Pragma("unroll") for (int m = 0; m < 4; ++m) _Pragma("unroll") for (int n = 0; n < 2; ++n) _Pragma("unroll") for (int k = 0; k < 2; ++k) \
;         acc[ai][bj][m][n] = __builtin_amdgcn_mfma_f32_16x16x32_bf16(Bt[n][k], At[m][k], acc[ai][bj][m][n], 0, 0, 0); __builtin_amdgcn_s_setprio(0); } while (0)
; #define PG8_WAIT_V(n) asm volatile("s_waitcnt vmcnt(" #n ")" ::: "memory")
; #define PG8_WAIT_L(n) asm volatile("s_waitcnt lgkmcnt(" #n ")" ::: "memory")
; #define PG8_BAR __builtin_amdgcn_s_barrier()
; #define PG8_SCHED __builtin_amdgcn_sched_barrier(0)
; template <class Epi, class Sched, bool ALIGN_EPI = false, bool SP2 = false>
; __device__ __forceinline__ void gemm_phase(PG8_LAS unsigned char* lds, const Gemm g, const Sched& S, const Epi& E) {
;     ...
;             PG8_WAIT_V(8); PG8_WAIT_L(0); PG8_BAR; PG8_MMA(1, 0, At, B0); PG8_MMA(1, 1, At, B1); PG8_BAR; PG8_SCHED;
;             PG8_LDB(B0, 1, 0); PG8_LDB(B1, 1, 1); PG8_SCHED; PG8_LDA(At, 1, 0); PG8_STAGE(PG8_SA(0, 1), a2 + hstep, voffA);
;             PG8_WAIT_V(8); PG8_WAIT_L(0); PG8_BAR; PG8_MMA(0, 0, At, B0); PG8_MMA(0, 1, At, B1); PG8_BAR; PG8_SCHED;
	s_setprio 1
	s_waitcnt lgkmcnt(0)
	v_mfma_f32_16x16x32_bf16 v[60:63], v[128:131], v[160:163], v[60:63]
	v_mfma_f32_16x16x32_bf16 v[56:59], v[136:139], v[160:163], v[56:59]
	v_mfma_f32_16x16x32_bf16 v[52:55], v[128:131], v[168:171], v[52:55]
	v_mfma_f32_16x16x32_bf16 v[48:51], v[136:139], v[168:171], v[48:51]
	v_mfma_f32_16x16x32_bf16 v[44:47], v[128:131], v[176:179], v[44:47]
	v_mfma_f32_16x16x32_bf16 v[40:43], v[136:139], v[176:179], v[40:43]
	v_mfma_f32_16x16x32_bf16 v[36:39], v[128:131], v[184:187], v[36:39]
	v_mfma_f32_16x16x32_bf16 v[32:35], v[136:139], v[184:187], v[32:35]
	v_mfma_f32_16x16x32_bf16 v[60:63], v[132:135], v[164:167], v[60:63]
	v_mfma_f32_16x16x32_bf16 v[56:59], v[140:143], v[164:167], v[56:59]
	v_mfma_f32_16x16x32_bf16 v[52:55], v[132:135], v[172:175], v[52:55]
	v_mfma_f32_16x16x32_bf16 v[48:51], v[140:143], v[172:175], v[48:51]
	v_mfma_f32_16x16x32_bf16 v[44:47], v[132:135], v[180:183], v[44:47]
	v_mfma_f32_16x16x32_bf16 v[40:43], v[140:143], v[180:183], v[40:43]
	v_mfma_f32_16x16x32_bf16 v[36:39], v[132:135], v[188:191], v[36:39]
	v_mfma_f32_16x16x32_bf16 v[32:35], v[140:143], v[188:191], v[32:35]
	s_setprio 0
	s_setprio 1
	v_mfma_f32_16x16x32_bf16 v[28:31], v[144:147], v[160:163], v[28:31]
	v_mfma_f32_16x16x32_bf16 v[24:27], v[152:155], v[160:163], v[24:27]
	v_mfma_f32_16x16x32_bf16 v[20:23], v[144:147], v[168:171], v[20:23]
	v_mfma_f32_16x16x32_bf16 v[16:19], v[152:155], v[168:171], v[16:19]
	v_mfma_f32_16x16x32_bf16 v[12:15], v[144:147], v[176:179], v[12:15]
	v_mfma_f32_16x16x32_bf16 v[8:11], v[152:155], v[176:179], v[8:11]
	v_mfma_f32_16x16x32_bf16 v[4:7], v[144:147], v[184:187], v[4:7]
	v_mfma_f32_16x16x32_bf16 v[0:3], v[152:155], v[184:187], v[0:3]
	v_mfma_f32_16x16x32_bf16 v[28:31], v[148:151], v[164:167], v[28:31]
	v_mfma_f32_16x16x32_bf16 v[24:27], v[156:159], v[164:167], v[24:27]
	v_mfma_f32_16x16x32_bf16 v[20:23], v[148:151], v[172:175], v[20:23]
	v_mfma_f32_16x16x32_bf16 v[16:19], v[156:159], v[172:175], v[16:19]
	v_mfma_f32_16x16x32_bf16 v[12:15], v[148:151], v[180:183], v[12:15]
	v_mfma_f32_16x16x32_bf16 v[8:11], v[156:159], v[180:183], v[8:11]
	v_mfma_f32_16x16x32_bf16 v[4:7], v[148:151], v[188:191], v[4:7]
	v_mfma_f32_16x16x32_bf16 v[0:3], v[156:159], v[188:191], v[0:3]
	s_setprio 0
	s_barrier
	s_add_i32 s77, 0, 0x18000
	s_add_i32 s78, 0, 0x1c000
	v_add_u32_e32 v140, s77, v246
	v_add_u32_e32 v156, s78, v246
	ds_read_b128 v[128:131], v140
	ds_read_b128 v[132:135], v140 offset:1024
	ds_read_b128 v[136:139], v140 offset:2048
	ds_read_b128 v[140:143], v140 offset:3072
	ds_read_b128 v[144:147], v156
	ds_read_b128 v[148:151], v156 offset:1024
	ds_read_b128 v[152:155], v156 offset:2048
	ds_read_b128 v[156:159], v156 offset:3072
	s_add_u32 s10, s52, 0x40000
	s_addc_u32 s11, s53, 0
	s_mov_b32 m0, s59
	v_lshl_add_u64 v[216:217], s[10:11], 0, v[200:201]
	ds_read_b128 v[160:163], v249 offset:32768
	ds_read_b128 v[164:167], v249 offset:33792
	ds_read_b128 v[168:171], v249 offset:34816
	ds_read_b128 v[172:175], v249 offset:35840
	ds_read_b128 v[176:179], v249 offset:36864
	ds_read_b128 v[180:183], v249 offset:37888
	ds_read_b128 v[184:187], v249 offset:38912
	ds_read_b128 v[188:191], v249 offset:39936
	global_load_lds_dwordx4 v[216:217], off
	v_lshl_add_u64 v[216:217], s[10:11], 0, v[196:197]
	s_mov_b32 m0, s60
	s_nop 0
	global_load_lds_dwordx4 v[216:217], off
	s_waitcnt vmcnt(8)
	s_waitcnt lgkmcnt(0)
	s_barrier
	s_setprio 1
	s_waitcnt lgkmcnt(0)
	v_mfma_f32_16x16x32_bf16 v[124:127], v[128:131], v[160:163], v[124:127]
	v_mfma_f32_16x16x32_bf16 v[120:123], v[136:139], v[160:163], v[120:123]
	v_mfma_f32_16x16x32_bf16 v[116:119], v[128:131], v[168:171], v[116:119]
	v_mfma_f32_16x16x32_bf16 v[112:115], v[136:139], v[168:171], v[112:115]
	v_mfma_f32_16x16x32_bf16 v[108:111], v[128:131], v[176:179], v[108:111]
	v_mfma_f32_16x16x32_bf16 v[104:107], v[136:139], v[176:179], v[104:107]
	v_mfma_f32_16x16x32_bf16 v[100:103], v[128:131], v[184:187], v[100:103]
	v_mfma_f32_16x16x32_bf16 v[96:99], v[136:139], v[184:187], v[96:99]
	v_mfma_f32_16x16x32_bf16 v[124:127], v[132:135], v[164:167], v[124:127]
	v_mfma_f32_16x16x32_bf16 v[120:123], v[140:143], v[164:167], v[120:123]
	v_mfma_f32_16x16x32_bf16 v[116:119], v[132:135], v[172:175], v[116:119]
	v_mfma_f32_16x16x32_bf16 v[112:115], v[140:143], v[172:175], v[112:115]
	v_mfma_f32_16x16x32_bf16 v[108:111], v[132:135], v[180:183], v[108:111]
	v_mfma_f32_16x16x32_bf16 v[104:107], v[140:143], v[180:183], v[104:107]
	v_mfma_f32_16x16x32_bf16 v[100:103], v[132:135], v[188:191], v[100:103]
	v_mfma_f32_16x16x32_bf16 v[96:99], v[140:143], v[188:191], v[96:99]
	s_setprio 0
	s_setprio 1
	v_mfma_f32_16x16x32_bf16 v[92:95], v[144:147], v[160:163], v[92:95]
	v_mfma_f32_16x16x32_bf16 v[88:91], v[152:155], v[160:163], v[88:91]
	v_mfma_f32_16x16x32_bf16 v[84:87], v[144:147], v[168:171], v[84:87]
	v_mfma_f32_16x16x32_bf16 v[80:83], v[152:155], v[168:171], v[80:83]
	v_mfma_f32_16x16x32_bf16 v[76:79], v[144:147], v[176:179], v[76:79]
	v_mfma_f32_16x16x32_bf16 v[72:75], v[152:155], v[176:179], v[72:75]
	v_mfma_f32_16x16x32_bf16 v[68:71], v[144:147], v[184:187], v[68:71]
	v_mfma_f32_16x16x32_bf16 v[64:67], v[152:155], v[184:187], v[64:67]
	v_mfma_f32_16x16x32_bf16 v[92:95], v[148:151], v[164:167], v[92:95]
	v_mfma_f32_16x16x32_bf16 v[88:91], v[156:159], v[164:167], v[88:91]
	v_mfma_f32_16x16x32_bf16 v[84:87], v[148:151], v[172:175], v[84:87]
	v_mfma_f32_16x16x32_bf16 v[80:83], v[156:159], v[172:175], v[80:83]
	v_mfma_f32_16x16x32_bf16 v[76:79], v[148:151], v[180:183], v[76:79]
	v_mfma_f32_16x16x32_bf16 v[72:75], v[156:159], v[180:183], v[72:75]
	v_mfma_f32_16x16x32_bf16 v[68:71], v[148:151], v[188:191], v[68:71]
	v_mfma_f32_16x16x32_bf16 v[64:67], v[156:159], v[188:191], v[64:67]
	s_setprio 0
	s_barrier
; #define PG8_STAGE(bufoff, gbase, voff) do { _Pragma("unroll") for (int _i = 0; _i < 2; ++_i) \
;         __builtin_amdgcn_global_load_lds((const unsigned*)((const char*)(gbase) + (voff)[_i]), (PG8_LAS unsigned*)(lds + (bufoff) + ldsw + _i * 8192), 16, 0, 0); } while (0)
; #define PG8_LDA(dst, b, h) do { _Pragma("unroll") for (int m = 0; m < 4; ++m) _Pragma("unroll") for (int k = 0; k < 2; ++k) dst[m][k] = *(const PG8_LAS bf16x8*)(lds + PG8_SA(b, h) + aoff + m * 2048 + k * 1024); } while (0)
; #define PG8_MMA(ai, bj, At, Bt) do { __builtin_amdgcn_s_setprio(1); _Pragma("unroll") for (int m = 0; m < 4; ++m) _Pragma("unroll") for (int n = 0; n < 2; ++n) _Pragma("unroll") for (int k = 0; k < 2; ++k) \
;         acc[ai][bj][m][n] = __builtin_amdgcn_mfma_f32_16x16x32_bf16(Bt[n][k], At[m][k], acc[ai][bj][m][n], 0, 0, 0); __builtin_amdgcn_s_setprio(0); } while (0)
; #define PG8_WAIT_V(n) asm volatile("s_waitcnt vmcnt(" #n ")" ::: "memory")
; #define PG8_WAIT_L(n) asm volatile("s_waitcnt lgkmcnt(" #n ")" ::: "memory")
; #define PG8_BAR __builtin_amdgcn_s_barrier()
; #define PG8_SCHED __builtin_amdgcn_sched_barrier(0)
; template <class Epi, class Sched, bool ALIGN_EPI = false, bool SP2 = false>
; __device__ __forceinline__ void gemm_phase(PG8_LAS unsigned char* lds, const Gemm g, const Sched& S, const Epi& E) {
;     ...
;         for (int t = 0; t < nt; t += 2) {
;             const bool last = (t == nt - 2);
;     ...
;             PG8_LDA(At, 1, 1); PG8_STAGE(PG8_SB(1, 0), b3, voffB); PG8_STAGE(PG8_SB(1, 1), b3 + hstep, voffB); PG8_STAGE(PG8_SA(1, 0), a3, voffA);
;             PG8_WAIT_V(8); PG8_WAIT_L(0); PG8_BAR; PG8_MMA(1, 0, At, B0); PG8_MMA(1, 1, At, B1); PG8_BAR; PG8_SCHED;
	s_add_i32 s10, s77, s14
	v_lshl_add_u64 v[208:209], v[208:209], 0, s[36:37]
	s_mov_b32 m0, s10
	ds_read_b128 v[160:163], v249 offset:49152
	ds_read_b128 v[164:167], v249 offset:50176
	ds_read_b128 v[168:171], v249 offset:51200
	ds_read_b128 v[172:175], v249 offset:52224
	ds_read_b128 v[176:179], v249 offset:53248
	ds_read_b128 v[180:183], v249 offset:54272
	ds_read_b128 v[184:187], v249 offset:55296
	ds_read_b128 v[188:191], v249 offset:56320
	global_load_lds_dwordx4 v[208:209], off
	s_add_i32 m0, s10, 0x2000
	s_add_u32 s10, s50, 0x40080
	v_lshl_add_u64 v[208:209], v[210:211], 0, s[36:37]
	s_addc_u32 s11, s51, 0
	s_add_i32 s50, s78, s14
	global_load_lds_dwordx4 v[208:209], off
	v_lshl_add_u64 v[208:209], s[10:11], 0, v[198:199]
	s_mov_b32 m0, s50
	s_nop 0
	global_load_lds_dwordx4 v[208:209], off
	v_lshl_add_u64 v[208:209], s[10:11], 0, v[194:195]
	s_add_i32 m0, s50, 0x2000
	s_nop 0
	global_load_lds_dwordx4 v[208:209], off
	v_lshl_add_u64 v[208:209], v[212:213], 0, s[36:37]
	s_mov_b32 m0, s65
	s_nop 0
	global_load_lds_dwordx4 v[208:209], off
	v_lshl_add_u64 v[208:209], v[214:215], 0, s[36:37]
	s_mov_b32 m0, s66
	s_nop 0
	global_load_lds_dwordx4 v[208:209], off
	s_waitcnt vmcnt(8)
	s_waitcnt lgkmcnt(0)
	s_barrier
	s_setprio 1
	s_waitcnt lgkmcnt(0)
	v_mfma_f32_16x16x32_bf16 v[60:63], v[128:131], v[160:163], v[60:63]
	v_mfma_f32_16x16x32_bf16 v[56:59], v[136:139], v[160:163], v[56:59]
	v_mfma_f32_16x16x32_bf16 v[52:55], v[128:131], v[168:171], v[52:55]
	v_mfma_f32_16x16x32_bf16 v[48:51], v[136:139], v[168:171], v[48:51]
	v_mfma_f32_16x16x32_bf16 v[44:47], v[128:131], v[176:179], v[44:47]
	v_mfma_f32_16x16x32_bf16 v[40:43], v[136:139], v[176:179], v[40:43]
	v_mfma_f32_16x16x32_bf16 v[36:39], v[128:131], v[184:187], v[36:39]
	v_mfma_f32_16x16x32_bf16 v[32:35], v[136:139], v[184:187], v[32:35]
	v_mfma_f32_16x16x32_bf16 v[60:63], v[132:135], v[164:167], v[60:63]
	v_mfma_f32_16x16x32_bf16 v[56:59], v[140:143], v[164:167], v[56:59]
	v_mfma_f32_16x16x32_bf16 v[52:55], v[132:135], v[172:175], v[52:55]
	v_mfma_f32_16x16x32_bf16 v[48:51], v[140:143], v[172:175], v[48:51]
	v_mfma_f32_16x16x32_bf16 v[44:47], v[132:135], v[180:183], v[44:47]
	v_mfma_f32_16x16x32_bf16 v[40:43], v[140:143], v[180:183], v[40:43]
	v_mfma_f32_16x16x32_bf16 v[36:39], v[132:135], v[188:191], v[36:39]
	v_mfma_f32_16x16x32_bf16 v[32:35], v[140:143], v[188:191], v[32:35]
	s_setprio 0
	s_setprio 1
	v_mfma_f32_16x16x32_bf16 v[28:31], v[144:147], v[160:163], v[28:31]
	v_mfma_f32_16x16x32_bf16 v[24:27], v[152:155], v[160:163], v[24:27]
	v_mfma_f32_16x16x32_bf16 v[20:23], v[144:147], v[168:171], v[20:23]
	v_mfma_f32_16x16x32_bf16 v[16:19], v[152:155], v[168:171], v[16:19]
	v_mfma_f32_16x16x32_bf16 v[12:15], v[144:147], v[176:179], v[12:15]
	v_mfma_f32_16x16x32_bf16 v[8:11], v[152:155], v[176:179], v[8:11]
	v_mfma_f32_16x16x32_bf16 v[4:7], v[144:147], v[184:187], v[4:7]
	v_mfma_f32_16x16x32_bf16 v[0:3], v[152:155], v[184:187], v[0:3]
	v_mfma_f32_16x16x32_bf16 v[28:31], v[148:151], v[164:167], v[28:31]
	v_mfma_f32_16x16x32_bf16 v[24:27], v[156:159], v[164:167], v[24:27]
	v_mfma_f32_16x16x32_bf16 v[20:23], v[148:151], v[172:175], v[20:23]
	v_mfma_f32_16x16x32_bf16 v[16:19], v[156:159], v[172:175], v[16:19]
	v_mfma_f32_16x16x32_bf16 v[12:15], v[148:151], v[180:183], v[12:15]
	v_mfma_f32_16x16x32_bf16 v[8:11], v[156:159], v[180:183], v[8:11]
	v_mfma_f32_16x16x32_bf16 v[4:7], v[148:151], v[188:191], v[4:7]
	v_mfma_f32_16x16x32_bf16 v[0:3], v[156:159], v[188:191], v[0:3]
	s_setprio 0
	s_add_i32 s76, s76, 2
	s_add_u32 s34, s34, 0x100
	s_addc_u32 s35, s35, 0
	s_add_u32 s19, s19, 0x100
	s_addc_u32 s75, s75, 0
	s_cmp_gt_u32 s76, 5
	s_cbranch_scc1 .Llast_g3
	s_barrier
	s_branch .LBB0_488
.Llast_g3:
	s_and_b64 vcc, exec, s[24:25]
	s_cbranch_vccz .LBB0_491
	s_barrier

; #define PG8_STAGE(bufoff, gbase, voff) do { _Pragma("unroll") for (int _i = 0; _i < 2; ++_i) \
;         __builtin_amdgcn_global_load_lds((const unsigned*)((const char*)(gbase) + (voff)[_i]), (PG8_LAS unsigned*)(lds + (bufoff) + ldsw + _i * 8192), 16, 0, 0); } while (0)
; #define PG8_LDA(dst, b, h) do { _Pragma("unroll") for (int m = 0; m < 4; ++m) _Pragma("unroll") for (int k = 0; k < 2; ++k) dst[m][k] = *(const PG8_LAS bf16x8*)(lds + PG8_SA(b, h) + aoff + m * 2048 + k * 1024); } while (0)
; #define PG8_LDB(dst, b, h) do { _Pragma("unroll") for (int n = 0; n < 2; ++n) _Pragma("unroll") for (int k = 0; k < 2; ++k) dst[n][k] = *(const PG8_LAS bf16x8*)(lds + PG8_SB(b, h) + boff + n * 2048 + k * 1024); } while (0)
; #define PG8_MMA(ai, bj, At, Bt) do { __builtin_amdgcn_s_setprio(1); _Pragma("unroll") for (int m = 0; m < 4; ++m) _Pragma("unroll") for (int n = 0; n < 2; ++n) _Pragma("unroll") for (int k = 0; k < 2; ++k) \
;         acc[ai][bj][m][n] = __builtin_amdgcn_mfma_f32_16x16x32_bf16(Bt[n][k], At[m][k], acc[ai][bj][m][n], 0, 0, 0); __builtin_amdgcn_s_setprio(0); } while (0)
; #define PG8_WAIT_V(n) asm volatile("s_waitcnt vmcnt(" #n ")" ::: "memory")
; #define PG8_WAIT_L(n) asm volatile("s_waitcnt lgkmcnt(" #n ")" ::: "memory")
; template <class Epi, class Sched, bool ALIGN_EPI = false, bool SP2 = false>
; __device__ __forceinline__ void gemm_phase(PG8_LAS unsigned char* lds, const Gemm g, const Sched& S, const Epi& E) {
;     ...
;             const bool last = (t == nt - 2);
;             const char* a1 = cA + (size_t)(t + 1) * kstep;
;             const char* a2 = last ? nA : cA + (size_t)(t + 2) * kstep; const char* b2 = last ? nB : cB + (size_t)(t + 2) * kstep;
;             const char* a3 = a2 + kstep; const char* b3 = b2 + kstep;
;             if (last && has_next) S.a_ready(nxt);
;             if constexpr (SP2) {
;             PG8_LDB(B0, 0, 0); PG8_LDB(B1, 0, 1); PG8_SCHED; PG8_LDA(At, 0, 0); PG8_STAGE(PG8_SA(1, 1), a1 + hstep, voffA);
;             PG8_WAIT_V(8); PG8_WAIT_L(0); PG8_BAR; PG8_MMA(0, 0, At, B0); PG8_MMA(0, 1, At, B1); PG8_BAR; PG8_SCHED;
;             PG8_LDA(At, 0, 1); PG8_STAGE(PG8_SB(0, 0), b2, voffB); PG8_STAGE(PG8_SB(0, 1), b2 + hstep, voffB); PG8_STAGE(PG8_SA(0, 0), a2, voffA);
;             PG8_WAIT_V(8); PG8_WAIT_L(0); PG8_BAR; PG8_MMA(1, 0, At, B0); PG8_MMA(1, 1, At, B1); PG8_BAR; PG8_SCHED;
.LBB0_577:
	s_add_u32 s10, s44, 0xfffc0080
	s_addc_u32 s11, s45, -1
	s_add_i32 s64, 0, 0x10000
	s_cmp_eq_u32 s63, 12
	s_cselect_b32 s49, s29, s11
	s_cselect_b32 s48, s43, s10
	v_add_u32_e32 v146, s64, v149
	s_cselect_b32 s47, s27, s62
	s_cselect_b32 s46, s60, s61
	s_add_i32 s65, 0, 0x14000
	ds_read_b128 v[128:131], v146
	ds_read_b128 v[154:157], v146 offset:1024
	ds_read_b128 v[158:161], v146 offset:2048
	ds_read_b128 v[162:165], v146 offset:3072
	v_add_u32_e32 v146, s65, v149
	ds_read_b128 v[166:169], v146
	ds_read_b128 v[170:173], v146 offset:1024
	ds_read_b128 v[174:177], v146 offset:2048
	ds_read_b128 v[178:181], v146 offset:3072
	v_lshl_add_u64 v[190:191], s[44:45], 0, v[142:143]
	s_add_i32 m0, s51, 0xc000
	ds_read_b128 v[182:185], v153
	ds_read_b128 v[186:189], v153 offset:1024
	ds_read_b128 v[194:197], v153 offset:2048
	ds_read_b128 v[198:201], v153 offset:3072
	ds_read_b128 v[202:205], v153 offset:4096
	ds_read_b128 v[206:209], v153 offset:5120
	ds_read_b128 v[210:213], v153 offset:6144
	ds_read_b128 v[214:217], v153 offset:7168
	global_load_lds_dwordx4 v[190:191], off
	v_lshl_add_u64 v[190:191], s[44:45], 0, v[144:145]
	s_add_i32 m0, s51, 0xe000
	s_nop 0
	global_load_lds_dwordx4 v[190:191], off
	s_waitcnt vmcnt(8)
	s_waitcnt lgkmcnt(0)
	s_barrier
	s_setprio 1
	s_waitcnt lgkmcnt(0)
	v_mfma_f32_16x16x32_bf16 v[124:127], v[128:131], v[182:185], v[124:127]
	v_mfma_f32_16x16x32_bf16 v[116:119], v[158:161], v[182:185], v[116:119]
	v_mfma_f32_16x16x32_bf16 v[108:111], v[128:131], v[194:197], v[108:111]
	v_mfma_f32_16x16x32_bf16 v[100:103], v[158:161], v[194:197], v[100:103]
	v_mfma_f32_16x16x32_bf16 v[92:95], v[128:131], v[202:205], v[92:95]
	v_mfma_f32_16x16x32_bf16 v[84:87], v[158:161], v[202:205], v[84:87]
	v_mfma_f32_16x16x32_bf16 v[76:79], v[128:131], v[210:213], v[76:79]
	v_mfma_f32_16x16x32_bf16 v[68:71], v[158:161], v[210:213], v[68:71]
	v_mfma_f32_16x16x32_bf16 v[124:127], v[154:157], v[186:189], v[124:127]
	v_mfma_f32_16x16x32_bf16 v[116:119], v[162:165], v[186:189], v[116:119]
	v_mfma_f32_16x16x32_bf16 v[108:111], v[154:157], v[198:201], v[108:111]
	v_mfma_f32_16x16x32_bf16 v[100:103], v[162:165], v[198:201], v[100:103]
	v_mfma_f32_16x16x32_bf16 v[92:95], v[154:157], v[206:209], v[92:95]
	v_mfma_f32_16x16x32_bf16 v[84:87], v[162:165], v[206:209], v[84:87]
	v_mfma_f32_16x16x32_bf16 v[76:79], v[154:157], v[214:217], v[76:79]
	v_mfma_f32_16x16x32_bf16 v[68:71], v[162:165], v[214:217], v[68:71]
	s_setprio 0
	s_setprio 1
	v_mfma_f32_16x16x32_bf16 v[120:123], v[166:169], v[182:185], v[120:123]
	v_mfma_f32_16x16x32_bf16 v[112:115], v[174:177], v[182:185], v[112:115]
	v_mfma_f32_16x16x32_bf16 v[104:107], v[166:169], v[194:197], v[104:107]
	v_mfma_f32_16x16x32_bf16 v[96:99], v[174:177], v[194:197], v[96:99]
	v_mfma_f32_16x16x32_bf16 v[88:91], v[166:169], v[202:205], v[88:91]
	v_mfma_f32_16x16x32_bf16 v[80:83], v[174:177], v[202:205], v[80:83]
	v_mfma_f32_16x16x32_bf16 v[72:75], v[166:169], v[210:213], v[72:75]
	v_mfma_f32_16x16x32_bf16 v[64:67], v[174:177], v[210:213], v[64:67]
	v_mfma_f32_16x16x32_bf16 v[120:123], v[170:173], v[186:189], v[120:123]
	v_mfma_f32_16x16x32_bf16 v[112:115], v[178:181], v[186:189], v[112:115]
	v_mfma_f32_16x16x32_bf16 v[104:107], v[170:173], v[198:201], v[104:107]
	v_mfma_f32_16x16x32_bf16 v[96:99], v[178:181], v[198:201], v[96:99]
	v_mfma_f32_16x16x32_bf16 v[88:91], v[170:173], v[206:209], v[88:91]
	v_mfma_f32_16x16x32_bf16 v[80:83], v[178:181], v[206:209], v[80:83]
	v_mfma_f32_16x16x32_bf16 v[72:75], v[170:173], v[214:217], v[72:75]
	v_mfma_f32_16x16x32_bf16 v[64:67], v[178:181], v[214:217], v[64:67]
	s_setprio 0
	s_barrier
	s_add_i32 s10, s64, s19
	v_lshl_add_u64 v[190:191], s[46:47], 0, v[136:137]
	s_mov_b32 m0, s10
	ds_read_b128 v[182:185], v153 offset:16384
	ds_read_b128 v[186:189], v153 offset:17408
	ds_read_b128 v[194:197], v153 offset:18432
	ds_read_b128 v[198:201], v153 offset:19456
	ds_read_b128 v[202:205], v153 offset:20480
	ds_read_b128 v[206:209], v153 offset:21504
	ds_read_b128 v[210:213], v153 offset:22528
	ds_read_b128 v[214:217], v153 offset:23552
	global_load_lds_dwordx4 v[190:191], off
	s_add_i32 m0, s10, 0x2000
	s_add_u32 s10, s46, 0x40000
	v_lshl_add_u64 v[218:219], s[46:47], 0, v[132:133]
	s_addc_u32 s11, s47, 0
	s_add_i32 s64, s65, s19
	global_load_lds_dwordx4 v[218:219], off
	v_lshl_add_u64 v[220:221], s[10:11], 0, v[136:137]
	s_mov_b32 m0, s64
	v_lshl_add_u64 v[222:223], s[48:49], 0, v[134:135]
	global_load_lds_dwordx4 v[220:221], off
	v_lshl_add_u64 v[220:221], s[10:11], 0, v[132:133]
	s_add_i32 m0, s64, 0x2000
	s_nop 0
	global_load_lds_dwordx4 v[220:221], off
	v_lshl_add_u64 v[220:221], s[48:49], 0, v[138:139]
	s_mov_b32 m0, s51
	s_nop 0
	global_load_lds_dwordx4 v[220:221], off
	s_mov_b32 m0, s52
	s_nop 0
	global_load_lds_dwordx4 v[222:223], off
	s_waitcnt vmcnt(8)
	s_waitcnt lgkmcnt(0)
	s_barrier
; #define PG8_STAGE(bufoff, gbase, voff) do { _Pragma("unroll") for (int _i = 0; _i < 2; ++_i) \
;         __builtin_amdgcn_global_load_lds((const unsigned*)((const char*)(gbase) + (voff)[_i]), (PG8_LAS unsigned*)(lds + (bufoff) + ldsw + _i * 8192), 16, 0, 0); } while (0)
; #define PG8_LDA(dst, b, h) do { _Pragma("unroll") for (int m = 0; m < 4; ++m) _Pragma("unroll") for (int k = 0; k < 2; ++k) dst[m][k] = *(const PG8_LAS bf16x8*)(lds + PG8_SA(b, h) + aoff + m * 2048 + k * 1024); } while (0)
; #define PG8_LDB(dst, b, h) do { _Pragma("unroll") for (int n = 0; n < 2; ++n) _Pragma("unroll") for (int k = 0; k < 2; ++k) dst[n][k] = *(const PG8_LAS bf16x8*)(lds + PG8_SB(b, h) + boff + n * 2048 + k * 1024); } while (0)
; #define PG8_MMA(ai, bj, At, Bt) do { __builtin_amdgcn_s_setprio(1); _Pragma("unroll") for (int m = 0; m < 4; ++m) _Pragma("unroll") for (int n = 0; n < 2; ++n) _Pragma("unroll") for (int k = 0; k < 2; ++k) \
;         acc[ai][bj][m][n] = __builtin_amdgcn_mfma_f32_16x16x32_bf16(Bt[n][k], At[m][k], acc[ai][bj][m][n], 0, 0, 0); __builtin_amdgcn_s_setprio(0); } while (0)
; #define PG8_WAIT_V(n) asm volatile("s_waitcnt vmcnt(" #n ")" ::: "memory")
; #define PG8_WAIT_L(n) asm volatile("s_waitcnt lgkmcnt(" #n ")" ::: "memory")
; #define PG8_BAR __builtin_amdgcn_s_barrier()
; #define PG8_SCHED __builtin_amdgcn_sched_barrier(0)
; template <class Epi, class Sched, bool ALIGN_EPI = false, bool SP2 = false>
; __device__ __forceinline__ void gemm_phase(PG8_LAS unsigned char* lds, const Gemm g, const Sched& S, const Epi& E) {
;     ...
;             PG8_WAIT_V(8); PG8_WAIT_L(0); PG8_BAR; PG8_MMA(1, 0, At, B0); PG8_MMA(1, 1, At, B1); PG8_BAR; PG8_SCHED;
;             PG8_LDB(B0, 1, 0); PG8_LDB(B1, 1, 1); PG8_SCHED; PG8_LDA(At, 1, 0); PG8_STAGE(PG8_SA(0, 1), a2 + hstep, voffA);
;             PG8_WAIT_V(8); PG8_WAIT_L(0); PG8_BAR; PG8_MMA(0, 0, At, B0); PG8_MMA(0, 1, At, B1); PG8_BAR; PG8_SCHED;
	s_setprio 1
	s_waitcnt lgkmcnt(0)
	v_mfma_f32_16x16x32_bf16 v[60:63], v[128:131], v[182:185], v[60:63]
	v_mfma_f32_16x16x32_bf16 v[52:55], v[158:161], v[182:185], v[52:55]
	v_mfma_f32_16x16x32_bf16 v[44:47], v[128:131], v[194:197], v[44:47]
	v_mfma_f32_16x16x32_bf16 v[36:39], v[158:161], v[194:197], v[36:39]
	v_mfma_f32_16x16x32_bf16 v[28:31], v[128:131], v[202:205], v[28:31]
	v_mfma_f32_16x16x32_bf16 v[20:23], v[158:161], v[202:205], v[20:23]
	v_mfma_f32_16x16x32_bf16 v[12:15], v[128:131], v[210:213], v[12:15]
	v_mfma_f32_16x16x32_bf16 v[4:7], v[158:161], v[210:213], v[4:7]
	v_mfma_f32_16x16x32_bf16 v[60:63], v[154:157], v[186:189], v[60:63]
	v_mfma_f32_16x16x32_bf16 v[52:55], v[162:165], v[186:189], v[52:55]
	v_mfma_f32_16x16x32_bf16 v[44:47], v[154:157], v[198:201], v[44:47]
	v_mfma_f32_16x16x32_bf16 v[36:39], v[162:165], v[198:201], v[36:39]
	v_mfma_f32_16x16x32_bf16 v[28:31], v[154:157], v[206:209], v[28:31]
	v_mfma_f32_16x16x32_bf16 v[20:23], v[162:165], v[206:209], v[20:23]
	v_mfma_f32_16x16x32_bf16 v[12:15], v[154:157], v[214:217], v[12:15]
	v_mfma_f32_16x16x32_bf16 v[4:7], v[162:165], v[214:217], v[4:7]
	s_setprio 0
	s_setprio 1
	v_mfma_f32_16x16x32_bf16 v[56:59], v[166:169], v[182:185], v[56:59]
	v_mfma_f32_16x16x32_bf16 v[48:51], v[174:177], v[182:185], v[48:51]
	v_mfma_f32_16x16x32_bf16 v[40:43], v[166:169], v[194:197], v[40:43]
	v_mfma_f32_16x16x32_bf16 v[32:35], v[174:177], v[194:197], v[32:35]
	v_mfma_f32_16x16x32_bf16 v[24:27], v[166:169], v[202:205], v[24:27]
	v_mfma_f32_16x16x32_bf16 v[16:19], v[174:177], v[202:205], v[16:19]
	v_mfma_f32_16x16x32_bf16 v[8:11], v[166:169], v[210:213], v[8:11]
	v_mfma_f32_16x16x32_bf16 v[0:3], v[174:177], v[210:213], v[0:3]
	v_mfma_f32_16x16x32_bf16 v[56:59], v[170:173], v[186:189], v[56:59]
	v_mfma_f32_16x16x32_bf16 v[48:51], v[178:181], v[186:189], v[48:51]
	v_mfma_f32_16x16x32_bf16 v[40:43], v[170:173], v[198:201], v[40:43]
	v_mfma_f32_16x16x32_bf16 v[32:35], v[178:181], v[198:201], v[32:35]
	v_mfma_f32_16x16x32_bf16 v[24:27], v[170:173], v[206:209], v[24:27]
	v_mfma_f32_16x16x32_bf16 v[16:19], v[178:181], v[206:209], v[16:19]
	v_mfma_f32_16x16x32_bf16 v[8:11], v[170:173], v[214:217], v[8:11]
	v_mfma_f32_16x16x32_bf16 v[0:3], v[178:181], v[214:217], v[0:3]
	s_setprio 0
	s_barrier
	s_add_i32 s64, 0, 0x18000
	v_add_u32_e32 v146, s64, v149
	s_add_i32 s65, 0, 0x1c000
	ds_read_b128 v[128:131], v146
	ds_read_b128 v[154:157], v146 offset:1024
	ds_read_b128 v[158:161], v146 offset:2048
	ds_read_b128 v[162:165], v146 offset:3072
	v_add_u32_e32 v146, s65, v149
	ds_read_b128 v[166:169], v146
	ds_read_b128 v[170:173], v146 offset:1024
	ds_read_b128 v[174:177], v146 offset:2048
	ds_read_b128 v[178:181], v146 offset:3072
	s_add_u32 s10, s48, 0x40000
	s_addc_u32 s11, s49, 0
	s_mov_b32 m0, s53
	v_lshl_add_u64 v[224:225], s[10:11], 0, v[138:139]
	ds_read_b128 v[182:185], v153 offset:32768
	ds_read_b128 v[186:189], v153 offset:33792
	ds_read_b128 v[194:197], v153 offset:34816
	ds_read_b128 v[198:201], v153 offset:35840
	ds_read_b128 v[202:205], v153 offset:36864
	ds_read_b128 v[206:209], v153 offset:37888
	ds_read_b128 v[210:213], v153 offset:38912
	ds_read_b128 v[214:217], v153 offset:39936
	global_load_lds_dwordx4 v[224:225], off
	v_lshl_add_u64 v[224:225], s[10:11], 0, v[134:135]
	s_mov_b32 m0, s54
	s_nop 0
	global_load_lds_dwordx4 v[224:225], off
	s_waitcnt vmcnt(8)
	s_waitcnt lgkmcnt(0)
	s_barrier
	s_setprio 1
	s_waitcnt lgkmcnt(0)
	v_mfma_f32_16x16x32_bf16 v[124:127], v[128:131], v[182:185], v[124:127]
	v_mfma_f32_16x16x32_bf16 v[116:119], v[158:161], v[182:185], v[116:119]
	v_mfma_f32_16x16x32_bf16 v[108:111], v[128:131], v[194:197], v[108:111]
	v_mfma_f32_16x16x32_bf16 v[100:103], v[158:161], v[194:197], v[100:103]
	v_mfma_f32_16x16x32_bf16 v[92:95], v[128:131], v[202:205], v[92:95]
	v_mfma_f32_16x16x32_bf16 v[84:87], v[158:161], v[202:205], v[84:87]
	v_mfma_f32_16x16x32_bf16 v[76:79], v[128:131], v[210:213], v[76:79]
	v_mfma_f32_16x16x32_bf16 v[68:71], v[158:161], v[210:213], v[68:71]
	v_mfma_f32_16x16x32_bf16 v[124:127], v[154:157], v[186:189], v[124:127]
	v_mfma_f32_16x16x32_bf16 v[116:119], v[162:165], v[186:189], v[116:119]
	v_mfma_f32_16x16x32_bf16 v[108:111], v[154:157], v[198:201], v[108:111]
	v_mfma_f32_16x16x32_bf16 v[100:103], v[162:165], v[198:201], v[100:103]
	v_mfma_f32_16x16x32_bf16 v[92:95], v[154:157], v[206:209], v[92:95]
	v_mfma_f32_16x16x32_bf16 v[84:87], v[162:165], v[206:209], v[84:87]
	v_mfma_f32_16x16x32_bf16 v[76:79], v[154:157], v[214:217], v[76:79]
	v_mfma_f32_16x16x32_bf16 v[68:71], v[162:165], v[214:217], v[68:71]
	s_setprio 0
	s_setprio 1
	v_mfma_f32_16x16x32_bf16 v[120:123], v[166:169], v[182:185], v[120:123]
	v_mfma_f32_16x16x32_bf16 v[112:115], v[174:177], v[182:185], v[112:115]
	v_mfma_f32_16x16x32_bf16 v[104:107], v[166:169], v[194:197], v[104:107]
	v_mfma_f32_16x16x32_bf16 v[96:99], v[174:177], v[194:197], v[96:99]
	v_mfma_f32_16x16x32_bf16 v[88:91], v[166:169], v[202:205], v[88:91]
	v_mfma_f32_16x16x32_bf16 v[80:83], v[174:177], v[202:205], v[80:83]
	v_mfma_f32_16x16x32_bf16 v[72:75], v[166:169], v[210:213], v[72:75]
	v_mfma_f32_16x16x32_bf16 v[64:67], v[174:177], v[210:213], v[64:67]
	v_mfma_f32_16x16x32_bf16 v[120:123], v[170:173], v[186:189], v[120:123]
	v_mfma_f32_16x16x32_bf16 v[112:115], v[178:181], v[186:189], v[112:115]
	v_mfma_f32_16x16x32_bf16 v[104:107], v[170:173], v[198:201], v[104:107]
	v_mfma_f32_16x16x32_bf16 v[96:99], v[178:181], v[198:201], v[96:99]
	v_mfma_f32_16x16x32_bf16 v[88:91], v[170:173], v[206:209], v[88:91]
	v_mfma_f32_16x16x32_bf16 v[80:83], v[178:181], v[206:209], v[80:83]
	v_mfma_f32_16x16x32_bf16 v[72:75], v[170:173], v[214:217], v[72:75]
	v_mfma_f32_16x16x32_bf16 v[64:67], v[178:181], v[214:217], v[64:67]
	s_setprio 0
	s_barrier
; #define PG8_STAGE(bufoff, gbase, voff) do { _Pragma("unroll") for (int _i = 0; _i < 2; ++_i) \
;         __builtin_amdgcn_global_load_lds((const unsigned*)((const char*)(gbase) + (voff)[_i]), (PG8_LAS unsigned*)(lds + (bufoff) + ldsw + _i * 8192), 16, 0, 0); } while (0)
; #define PG8_LDA(dst, b, h) do { _Pragma("unroll") for (int m = 0; m < 4; ++m) _Pragma("unroll") for (int k = 0; k < 2; ++k) dst[m][k] = *(const PG8_LAS bf16x8*)(lds + PG8_SA(b, h) + aoff + m * 2048 + k * 1024); } while (0)
; #define PG8_MMA(ai, bj, At, Bt) do { __builtin_amdgcn_s_setprio(1); _Pragma("unroll") for (int m = 0; m < 4; ++m) _Pragma("unroll") for (int n = 0; n < 2; ++n) _Pragma("unroll") for (int k = 0; k < 2; ++k) \
;         acc[ai][bj][m][n] = __builtin_amdgcn_mfma_f32_16x16x32_bf16(Bt[n][k], At[m][k], acc[ai][bj][m][n], 0, 0, 0); __builtin_amdgcn_s_setprio(0); } while (0)
; #define PG8_WAIT_V(n) asm volatile("s_waitcnt vmcnt(" #n ")" ::: "memory")
; #define PG8_WAIT_L(n) asm volatile("s_waitcnt lgkmcnt(" #n ")" ::: "memory")
; #define PG8_BAR __builtin_amdgcn_s_barrier()
; #define PG8_SCHED __builtin_amdgcn_sched_barrier(0)
; template <class Epi, class Sched, bool ALIGN_EPI = false, bool SP2 = false>
; __device__ __forceinline__ void gemm_phase(PG8_LAS unsigned char* lds, const Gemm g, const Sched& S, const Epi& E) {
;     ...
;         for (int t = 0; t < nt; t += 2) {
;             const bool last = (t == nt - 2);
;     ...
;             PG8_LDA(At, 1, 1); PG8_STAGE(PG8_SB(1, 0), b3, voffB); PG8_STAGE(PG8_SB(1, 1), b3 + hstep, voffB); PG8_STAGE(PG8_SA(1, 0), a3, voffA);
;             PG8_WAIT_V(8); PG8_WAIT_L(0); PG8_BAR; PG8_MMA(1, 0, At, B0); PG8_MMA(1, 1, At, B1); PG8_BAR; PG8_SCHED;
	s_add_i32 s10, s64, s19
	v_lshl_add_u64 v[190:191], v[190:191], 0, s[36:37]
	s_mov_b32 m0, s10
	ds_read_b128 v[182:185], v153 offset:49152
	ds_read_b128 v[186:189], v153 offset:50176
	ds_read_b128 v[194:197], v153 offset:51200
	ds_read_b128 v[198:201], v153 offset:52224
	ds_read_b128 v[202:205], v153 offset:53248
	ds_read_b128 v[206:209], v153 offset:54272
	ds_read_b128 v[210:213], v153 offset:55296
	ds_read_b128 v[214:217], v153 offset:56320
	global_load_lds_dwordx4 v[190:191], off
	s_add_i32 m0, s10, 0x2000
	s_add_u32 s10, s46, 0x40080
	v_lshl_add_u64 v[190:191], v[218:219], 0, s[36:37]
	s_addc_u32 s11, s47, 0
	s_add_i32 s46, s65, s19
	global_load_lds_dwordx4 v[190:191], off
	v_lshl_add_u64 v[190:191], s[10:11], 0, v[136:137]
	s_mov_b32 m0, s46
	s_nop 0
	global_load_lds_dwordx4 v[190:191], off
	v_lshl_add_u64 v[190:191], s[10:11], 0, v[132:133]
	s_add_i32 m0, s46, 0x2000
	s_nop 0
	global_load_lds_dwordx4 v[190:191], off
	v_lshl_add_u64 v[190:191], v[220:221], 0, s[36:37]
	s_mov_b32 m0, s20
	s_nop 0
	global_load_lds_dwordx4 v[190:191], off
	v_lshl_add_u64 v[190:191], v[222:223], 0, s[36:37]
	s_mov_b32 m0, s55
	s_nop 0
	global_load_lds_dwordx4 v[190:191], off
	s_waitcnt vmcnt(8)
	s_waitcnt lgkmcnt(0)
	s_barrier
	s_setprio 1
	s_waitcnt lgkmcnt(0)
	v_mfma_f32_16x16x32_bf16 v[60:63], v[128:131], v[182:185], v[60:63]
	v_mfma_f32_16x16x32_bf16 v[52:55], v[158:161], v[182:185], v[52:55]
	v_mfma_f32_16x16x32_bf16 v[44:47], v[128:131], v[194:197], v[44:47]
	v_mfma_f32_16x16x32_bf16 v[36:39], v[158:161], v[194:197], v[36:39]
	v_mfma_f32_16x16x32_bf16 v[28:31], v[128:131], v[202:205], v[28:31]
	v_mfma_f32_16x16x32_bf16 v[20:23], v[158:161], v[202:205], v[20:23]
	v_mfma_f32_16x16x32_bf16 v[12:15], v[128:131], v[210:213], v[12:15]
	v_mfma_f32_16x16x32_bf16 v[4:7], v[158:161], v[210:213], v[4:7]
	v_mfma_f32_16x16x32_bf16 v[60:63], v[154:157], v[186:189], v[60:63]
	v_mfma_f32_16x16x32_bf16 v[52:55], v[162:165], v[186:189], v[52:55]
	v_mfma_f32_16x16x32_bf16 v[44:47], v[154:157], v[198:201], v[44:47]
	v_mfma_f32_16x16x32_bf16 v[36:39], v[162:165], v[198:201], v[36:39]
	v_mfma_f32_16x16x32_bf16 v[28:31], v[154:157], v[206:209], v[28:31]
	v_mfma_f32_16x16x32_bf16 v[20:23], v[162:165], v[206:209], v[20:23]
	v_mfma_f32_16x16x32_bf16 v[12:15], v[154:157], v[214:217], v[12:15]
	v_mfma_f32_16x16x32_bf16 v[4:7], v[162:165], v[214:217], v[4:7]
	s_setprio 0
	s_setprio 1
	v_mfma_f32_16x16x32_bf16 v[56:59], v[166:169], v[182:185], v[56:59]
	v_mfma_f32_16x16x32_bf16 v[48:51], v[174:177], v[182:185], v[48:51]
	v_mfma_f32_16x16x32_bf16 v[40:43], v[166:169], v[194:197], v[40:43]
	v_mfma_f32_16x16x32_bf16 v[32:35], v[174:177], v[194:197], v[32:35]
	v_mfma_f32_16x16x32_bf16 v[24:27], v[166:169], v[202:205], v[24:27]
	v_mfma_f32_16x16x32_bf16 v[16:19], v[174:177], v[202:205], v[16:19]
	v_mfma_f32_16x16x32_bf16 v[8:11], v[166:169], v[210:213], v[8:11]
	v_mfma_f32_16x16x32_bf16 v[0:3], v[174:177], v[210:213], v[0:3]
	v_mfma_f32_16x16x32_bf16 v[56:59], v[170:173], v[186:189], v[56:59]
	v_mfma_f32_16x16x32_bf16 v[48:51], v[178:181], v[186:189], v[48:51]
	v_mfma_f32_16x16x32_bf16 v[40:43], v[170:173], v[198:201], v[40:43]
	v_mfma_f32_16x16x32_bf16 v[32:35], v[178:181], v[198:201], v[32:35]
	v_mfma_f32_16x16x32_bf16 v[24:27], v[170:173], v[206:209], v[24:27]
	v_mfma_f32_16x16x32_bf16 v[16:19], v[178:181], v[206:209], v[16:19]
	v_mfma_f32_16x16x32_bf16 v[8:11], v[170:173], v[214:217], v[8:11]
	v_mfma_f32_16x16x32_bf16 v[0:3], v[178:181], v[214:217], v[0:3]
	s_setprio 0
	s_add_i32 s63, s63, 2
	s_add_u32 s44, s44, 0x100
	s_addc_u32 s45, s45, 0
	s_add_u32 s61, s61, 0x100
	s_addc_u32 s62, s62, 0
	s_cmp_gt_u32 s63, 13
	s_cbranch_scc1 .Llast_g4
	s_barrier
	s_branch .LBB0_577
